# v57 + K-loop: vmcnt and lgkmcnt waits merged into one s_waitcnt, s_setprio removed from the K-loops
# baseline (speedup 1.0000x reference)
; #define PG8_WAIT_V(n) asm volatile("s_waitcnt vmcnt(" #n ")" ::: "memory")
; #define PG8_WAIT_L(n) asm volatile("s_waitcnt lgkmcnt(" #n ")" ::: "memory")
; #define PG8_BAR __builtin_amdgcn_s_barrier()
; #define PG8_SCHED __builtin_amdgcn_sched_barrier(0)
;     ...
;             const char* a1 = cA + (size_t)(t + 1) * kstep;
;             const char* a2 = last ? nA : cA + (size_t)(t + 2) * kstep; const char* b2 = last ? nB : cB + (size_t)(t + 2) * kstep;
;             const char* a3 = a2 + kstep; const char* b3 = b2 + kstep;
;             if (last && has_next) S.a_ready(nxt);
;             if constexpr (SP2) {
;             PG8_LDB(B0, 0, 0); PG8_LDB(B1, 0, 1); PG8_SCHED; PG8_LDA(At, 0, 0); PG8_STAGE(PG8_SA(1, 1), a1 + hstepA, voffA);
;             PG8_WAIT_V(8); PG8_WAIT_L(0); PG8_BAR; PG8_MMA(0, 0, At, B0); PG8_MMA(0, 1, At, B1); PG8_BAR; PG8_SCHED;
;             if constexpr (!HALFU) PG8_LDA(At, 0, 1); PG8_STAGE(PG8_SB(0, 0), b2, voffB); PG8_STAGE(PG8_SB(0, 1), b2 + hstep, voffB); PG8_STAGE(PG8_SA(0, 0), a2, voffA);
;             PG8_WAIT_V(8); PG8_WAIT_L(0); PG8_BAR; if constexpr (!HALFU) { PG8_MMA(1, 0, At, B0); PG8_MMA(1, 1, At, B1); } PG8_BAR; PG8_SCHED;
.LBB0_317:
	s_add_u32 s98, s14, 0x80
	s_addc_u32 s99, s15, 0
	s_mov_b32 m0, s49
	s_nop 0
	global_load_lds_dwordx4 v252, s[98:99]
	s_mov_b32 m0, s50
	s_nop 0
	global_load_lds_dwordx4 v146, s[98:99]
	ds_read_b128 v[128:131], v155
	ds_read_b128 v[132:135], v155 offset:1024
	ds_read_b128 v[164:167], v155 offset:2048
	ds_read_b128 v[168:171], v155 offset:3072
	ds_read_b128 v[172:175], v156
	ds_read_b128 v[176:179], v156 offset:1024
	ds_read_b128 v[180:183], v156 offset:2048
	ds_read_b128 v[184:187], v156 offset:3072
	s_add_u32 s30, s14, 0x100
	s_addc_u32 s31, s15, 0
	s_cmp_eq_u32 s58, 28
	s_cselect_b32 s38, s23, s30
	s_cselect_b32 s39, s7, s31
	s_cselect_b32 s36, s55, s56
	s_cselect_b32 s37, s21, s57
	s_add_u32 s34, s38, 0x80
	s_addc_u32 s35, s39, 0
	s_add_u32 s14, s14, 0x80080
	s_addc_u32 s15, s15, 0
	s_add_i32 m0, s29, 0xc000
	ds_read_b128 v[188:191], v157
	ds_read_b128 v[192:195], v157 offset:1024
	ds_read_b128 v[196:199], v157 offset:2048
	ds_read_b128 v[200:203], v157 offset:3072
	ds_read_b128 v[204:207], v157 offset:4096
	ds_read_b128 v[208:211], v157 offset:5120
	ds_read_b128 v[212:215], v157 offset:6144
	ds_read_b128 v[216:219], v157 offset:7168
	global_load_lds_dwordx4 v252, s[14:15]
	s_add_i32 m0, s29, 0xe000
	s_nop 0
	global_load_lds_dwordx4 v146, s[14:15]
	s_waitcnt vmcnt(8) lgkmcnt(0)
	s_barrier
	v_mfma_scale_f32_16x16x128_f8f6f4 v[124:127], v[128:135], v[188:195], v[124:127], v158, v158 op_sel_hi:[0,0,0]
	v_mfma_scale_f32_16x16x128_f8f6f4 v[120:123], v[164:171], v[188:195], v[120:123], v158, v158 op_sel_hi:[0,0,0]
	v_mfma_scale_f32_16x16x128_f8f6f4 v[108:111], v[128:135], v[196:203], v[108:111], v158, v158 op_sel_hi:[0,0,0]
	v_mfma_scale_f32_16x16x128_f8f6f4 v[104:107], v[164:171], v[196:203], v[104:107], v158, v158 op_sel_hi:[0,0,0]
	v_mfma_scale_f32_16x16x128_f8f6f4 v[136:139], v[128:135], v[204:211], v[92:95], v158, v158 op_sel_hi:[0,0,0]
	v_mfma_scale_f32_16x16x128_f8f6f4 v[220:223], v[164:171], v[204:211], v[88:91], v158, v158 op_sel_hi:[0,0,0]
	v_mfma_scale_f32_16x16x128_f8f6f4 v[224:227], v[128:135], v[212:219], v[76:79], v158, v158 op_sel_hi:[0,0,0]
	v_mfma_scale_f32_16x16x128_f8f6f4 v[228:231], v[164:171], v[212:219], v[72:75], v158, v158 op_sel_hi:[0,0,0]
	v_mfma_scale_f32_16x16x128_f8f6f4 v[116:119], v[172:179], v[188:195], v[116:119], v158, v158 op_sel_hi:[0,0,0]
	v_mfma_scale_f32_16x16x128_f8f6f4 v[112:115], v[180:187], v[188:195], v[112:115], v158, v158 op_sel_hi:[0,0,0]
	v_mfma_scale_f32_16x16x128_f8f6f4 v[100:103], v[172:179], v[196:203], v[100:103], v158, v158 op_sel_hi:[0,0,0]
	v_mfma_scale_f32_16x16x128_f8f6f4 v[96:99], v[180:187], v[196:203], v[96:99], v158, v158 op_sel_hi:[0,0,0]
	v_mfma_scale_f32_16x16x128_f8f6f4 v[188:191], v[172:179], v[204:211], v[84:87], v158, v158 op_sel_hi:[0,0,0]
	v_mfma_scale_f32_16x16x128_f8f6f4 v[192:195], v[180:187], v[204:211], v[80:83], v158, v158 op_sel_hi:[0,0,0]
	v_mfma_scale_f32_16x16x128_f8f6f4 v[196:199], v[172:179], v[212:219], v[68:71], v158, v158 op_sel_hi:[0,0,0]
	v_mfma_scale_f32_16x16x128_f8f6f4 v[200:203], v[180:187], v[212:219], v[64:67], v158, v158 op_sel_hi:[0,0,0]
	s_barrier
	s_add_i32 s14, s53, s40
	s_mov_b32 m0, s14
	s_nop 1
	ds_read_b128 v[64:67], v157 offset:16384
	ds_read_b128 v[68:71], v157 offset:17408
	ds_read_b128 v[72:75], v157 offset:18432
	ds_read_b128 v[76:79], v157 offset:19456
	ds_read_b128 v[80:83], v157 offset:20480
	ds_read_b128 v[84:87], v157 offset:21504
	ds_read_b128 v[88:91], v157 offset:22528
	ds_read_b128 v[92:95], v157 offset:23552
	global_load_lds_dwordx4 v144, s[36:37]
	s_add_i32 m0, s14, 0x2000
	s_add_u32 s14, s36, 0x80000
	s_addc_u32 s15, s37, 0
	s_add_i32 s59, s54, s40
	global_load_lds_dwordx4 v148, s[36:37]
	s_mov_b32 m0, s59
	s_nop 0
	global_load_lds_dwordx4 v144, s[14:15]
	s_add_i32 m0, s59, 0x2000
	s_nop 0
	global_load_lds_dwordx4 v148, s[14:15]
	s_waitcnt vmcnt(4) lgkmcnt(0)
	s_barrier
	v_mfma_scale_f32_16x16x128_f8f6f4 v[60:63], v[128:135], v[64:71], v[60:63], v158, v158 op_sel_hi:[0,0,0]
	v_mfma_scale_f32_16x16x128_f8f6f4 v[56:59], v[164:171], v[64:71], v[56:59], v158, v158 op_sel_hi:[0,0,0]
	v_mfma_scale_f32_16x16x128_f8f6f4 v[204:207], v[128:135], v[72:79], v[44:47], v158, v158 op_sel_hi:[0,0,0]
	v_mfma_scale_f32_16x16x128_f8f6f4 v[208:211], v[164:171], v[72:79], v[40:43], v158, v158 op_sel_hi:[0,0,0]
	v_mfma_scale_f32_16x16x128_f8f6f4 v[212:215], v[128:135], v[80:87], v[28:31], v158, v158 op_sel_hi:[0,0,0]
	v_mfma_scale_f32_16x16x128_f8f6f4 v[216:219], v[164:171], v[80:87], v[24:27], v158, v158 op_sel_hi:[0,0,0]
	v_mfma_scale_f32_16x16x128_f8f6f4 v[232:235], v[128:135], v[88:95], v[12:15], v158, v158 op_sel_hi:[0,0,0]
	v_mfma_scale_f32_16x16x128_f8f6f4 v[236:239], v[164:171], v[88:95], v[8:11], v158, v158 op_sel_hi:[0,0,0]
	v_mfma_scale_f32_16x16x128_f8f6f4 v[52:55], v[172:179], v[64:71], v[52:55], v158, v158 op_sel_hi:[0,0,0]
	v_mfma_scale_f32_16x16x128_f8f6f4 v[48:51], v[180:187], v[64:71], v[48:51], v158, v158 op_sel_hi:[0,0,0]
	v_mfma_scale_f32_16x16x128_f8f6f4 v[240:243], v[172:179], v[72:79], v[36:39], v158, v158 op_sel_hi:[0,0,0]
	v_mfma_scale_f32_16x16x128_f8f6f4 v[244:247], v[180:187], v[72:79], v[32:35], v158, v158 op_sel_hi:[0,0,0]
	v_mfma_scale_f32_16x16x128_f8f6f4 v[248:251], v[172:179], v[80:87], v[20:23], v158, v158 op_sel_hi:[0,0,0]
	v_mfma_scale_f32_16x16x128_f8f6f4 v[150:153], v[180:187], v[80:87], v[16:19], v158, v158 op_sel_hi:[0,0,0]
	v_mfma_scale_f32_16x16x128_f8f6f4 v[160:163], v[172:179], v[88:95], v[4:7], v158, v158 op_sel_hi:[0,0,0]
	v_mfma_scale_f32_16x16x128_f8f6f4 v[140:143], v[180:187], v[88:95], v[0:3], v158, v158 op_sel_hi:[0,0,0]
	s_barrier
; #define PG8_WAIT_V(n) asm volatile("s_waitcnt vmcnt(" #n ")" ::: "memory")
; #define PG8_WAIT_L(n) asm volatile("s_waitcnt lgkmcnt(" #n ")" ::: "memory")
; #define PG8_BAR __builtin_amdgcn_s_barrier()
; #define PG8_SCHED __builtin_amdgcn_sched_barrier(0)
;     ...
;         for (int t = 0; t < nt; t += 2) {
;     ...
;             PG8_LDB(B0, 1, 0); PG8_LDB(B1, 1, 1); PG8_SCHED; PG8_LDA(At, 1, 0); PG8_STAGE(PG8_SA(0, 1), a2 + hstepA, voffA);
;             PG8_WAIT_V(8); PG8_WAIT_L(0); PG8_BAR; PG8_MMA(0, 0, At, B0); PG8_MMA(0, 1, At, B1); PG8_BAR; PG8_SCHED;
;             if constexpr (!HALFU) PG8_LDA(At, 1, 1); PG8_STAGE(PG8_SB(1, 0), b3, voffB); PG8_STAGE(PG8_SB(1, 1), b3 + hstep, voffB); PG8_STAGE(PG8_SA(1, 0), a3, voffA);
;             PG8_WAIT_V(8); PG8_WAIT_L(0); PG8_BAR; if constexpr (!HALFU) { PG8_MMA(1, 0, At, B0); PG8_MMA(1, 1, At, B1); } PG8_BAR; PG8_SCHED;
	s_mov_b32 m0, s29
	s_nop 0
	global_load_lds_dwordx4 v252, s[38:39]
	s_mov_b32 m0, s41
	s_nop 0
	global_load_lds_dwordx4 v146, s[38:39]
	s_add_i32 s59, 0, 0x18000
	v_add_u32_e32 v8, s59, v154
	s_add_i32 s60, 0, 0x1c000
	s_nop 1
	ds_read_b128 v[0:3], v8
	ds_read_b128 v[4:7], v8 offset:1024
	ds_read_b128 v[16:19], v8 offset:2048
	ds_read_b128 v[20:23], v8 offset:3072
	v_add_u32_e32 v8, s60, v154
	ds_read_b128 v[128:131], v8
	ds_read_b128 v[132:135], v8 offset:1024
	ds_read_b128 v[164:167], v8 offset:2048
	ds_read_b128 v[168:171], v8 offset:3072
	s_add_u32 s14, s38, 0x80000
	s_addc_u32 s15, s39, 0
	s_mov_b32 m0, s42
	ds_read_b128 v[8:11], v157 offset:32768
	ds_read_b128 v[12:15], v157 offset:33792
	ds_read_b128 v[24:27], v157 offset:34816
	ds_read_b128 v[28:31], v157 offset:35840
	ds_read_b128 v[32:35], v157 offset:36864
	ds_read_b128 v[36:39], v157 offset:37888
	ds_read_b128 v[40:43], v157 offset:38912
	ds_read_b128 v[44:47], v157 offset:39936
	global_load_lds_dwordx4 v252, s[14:15]
	s_mov_b32 m0, s43
	s_nop 0
	global_load_lds_dwordx4 v146, s[14:15]
	s_waitcnt vmcnt(8) lgkmcnt(0)
	s_barrier
	v_mfma_scale_f32_16x16x128_f8f6f4 v[124:127], v[0:7], v[8:15], v[124:127], v158, v158 op_sel_hi:[0,0,0]
	v_mfma_scale_f32_16x16x128_f8f6f4 v[120:123], v[16:23], v[8:15], v[120:123], v158, v158 op_sel_hi:[0,0,0]
	v_mfma_scale_f32_16x16x128_f8f6f4 v[108:111], v[0:7], v[24:31], v[108:111], v158, v158 op_sel_hi:[0,0,0]
	v_mfma_scale_f32_16x16x128_f8f6f4 v[104:107], v[16:23], v[24:31], v[104:107], v158, v158 op_sel_hi:[0,0,0]
	v_mfma_scale_f32_16x16x128_f8f6f4 v[92:95], v[0:7], v[32:39], v[136:139], v158, v158 op_sel_hi:[0,0,0]
	v_mfma_scale_f32_16x16x128_f8f6f4 v[88:91], v[16:23], v[32:39], v[220:223], v158, v158 op_sel_hi:[0,0,0]
	v_mfma_scale_f32_16x16x128_f8f6f4 v[76:79], v[0:7], v[40:47], v[224:227], v158, v158 op_sel_hi:[0,0,0]
	v_mfma_scale_f32_16x16x128_f8f6f4 v[72:75], v[16:23], v[40:47], v[228:231], v158, v158 op_sel_hi:[0,0,0]
	v_mfma_scale_f32_16x16x128_f8f6f4 v[116:119], v[128:135], v[8:15], v[116:119], v158, v158 op_sel_hi:[0,0,0]
	v_mfma_scale_f32_16x16x128_f8f6f4 v[112:115], v[164:171], v[8:15], v[112:115], v158, v158 op_sel_hi:[0,0,0]
	v_mfma_scale_f32_16x16x128_f8f6f4 v[100:103], v[128:135], v[24:31], v[100:103], v158, v158 op_sel_hi:[0,0,0]
	v_mfma_scale_f32_16x16x128_f8f6f4 v[96:99], v[164:171], v[24:31], v[96:99], v158, v158 op_sel_hi:[0,0,0]
	v_mfma_scale_f32_16x16x128_f8f6f4 v[84:87], v[128:135], v[32:39], v[188:191], v158, v158 op_sel_hi:[0,0,0]
	v_mfma_scale_f32_16x16x128_f8f6f4 v[80:83], v[164:171], v[32:39], v[192:195], v158, v158 op_sel_hi:[0,0,0]
	v_mfma_scale_f32_16x16x128_f8f6f4 v[68:71], v[128:135], v[40:47], v[196:199], v158, v158 op_sel_hi:[0,0,0]
	v_mfma_scale_f32_16x16x128_f8f6f4 v[64:67], v[164:171], v[40:47], v[200:203], v158, v158 op_sel_hi:[0,0,0]
	s_barrier
	s_add_u32 s14, s36, 0x80
	s_addc_u32 s15, s37, 0
	s_add_i32 s38, s59, s40
	s_mov_b32 m0, s38
	ds_read_b128 v[32:35], v157 offset:49152
	ds_read_b128 v[36:39], v157 offset:50176
	ds_read_b128 v[172:175], v157 offset:51200
	ds_read_b128 v[176:179], v157 offset:52224
	ds_read_b128 v[180:183], v157 offset:53248
	ds_read_b128 v[184:187], v157 offset:54272
	ds_read_b128 v[188:191], v157 offset:55296
	ds_read_b128 v[192:195], v157 offset:56320
	global_load_lds_dwordx4 v144, s[14:15]
	s_add_i32 m0, s38, 0x2000
	v_lshl_add_u64 v[8:9], s[14:15], 0, v[148:149]
	s_add_u32 s14, s36, 0x80080
	s_addc_u32 s15, s37, 0
	s_add_i32 s36, s60, s40
	global_load_lds_dwordx4 v[8:9], off
	s_mov_b32 m0, s36
	s_nop 0
	global_load_lds_dwordx4 v144, s[14:15]
	s_add_i32 m0, s36, 0x2000
	s_nop 0
	global_load_lds_dwordx4 v148, s[14:15]
	s_waitcnt vmcnt(4) lgkmcnt(0)
	s_barrier
	v_mfma_scale_f32_16x16x128_f8f6f4 v[60:63], v[0:7], v[32:39], v[60:63], v158, v158 op_sel_hi:[0,0,0]
	v_mfma_scale_f32_16x16x128_f8f6f4 v[56:59], v[16:23], v[32:39], v[56:59], v158, v158 op_sel_hi:[0,0,0]
	v_mfma_scale_f32_16x16x128_f8f6f4 v[44:47], v[0:7], v[172:179], v[204:207], v158, v158 op_sel_hi:[0,0,0]
	v_mfma_scale_f32_16x16x128_f8f6f4 v[40:43], v[16:23], v[172:179], v[208:211], v158, v158 op_sel_hi:[0,0,0]
	v_mfma_scale_f32_16x16x128_f8f6f4 v[28:31], v[0:7], v[180:187], v[212:215], v158, v158 op_sel_hi:[0,0,0]
	v_mfma_scale_f32_16x16x128_f8f6f4 v[24:27], v[16:23], v[180:187], v[216:219], v158, v158 op_sel_hi:[0,0,0]
	v_mfma_scale_f32_16x16x128_f8f6f4 v[12:15], v[0:7], v[188:195], v[232:235], v158, v158 op_sel_hi:[0,0,0]
	v_mfma_scale_f32_16x16x128_f8f6f4 v[8:11], v[16:23], v[188:195], v[236:239], v158, v158 op_sel_hi:[0,0,0]
	v_mfma_scale_f32_16x16x128_f8f6f4 v[52:55], v[128:135], v[32:39], v[52:55], v158, v158 op_sel_hi:[0,0,0]
	v_mfma_scale_f32_16x16x128_f8f6f4 v[48:51], v[164:171], v[32:39], v[48:51], v158, v158 op_sel_hi:[0,0,0]
	v_mfma_scale_f32_16x16x128_f8f6f4 v[36:39], v[128:135], v[172:179], v[240:243], v158, v158 op_sel_hi:[0,0,0]
	v_mfma_scale_f32_16x16x128_f8f6f4 v[32:35], v[164:171], v[172:179], v[244:247], v158, v158 op_sel_hi:[0,0,0]
	v_mfma_scale_f32_16x16x128_f8f6f4 v[20:23], v[128:135], v[180:187], v[248:251], v158, v158 op_sel_hi:[0,0,0]
	v_mfma_scale_f32_16x16x128_f8f6f4 v[16:19], v[164:171], v[180:187], v[150:153], v158, v158 op_sel_hi:[0,0,0]
	v_mfma_scale_f32_16x16x128_f8f6f4 v[4:7], v[128:135], v[188:195], v[160:163], v158, v158 op_sel_hi:[0,0,0]
	v_mfma_scale_f32_16x16x128_f8f6f4 v[0:3], v[164:171], v[188:195], v[140:143], v158, v158 op_sel_hi:[0,0,0]
	s_barrier
	s_add_i32 s58, s58, 2
	s_add_u32 s56, s56, 0x100
	s_addc_u32 s57, s57, 0
	s_cmp_gt_u32 s58, 29
	s_mov_b64 s[14:15], s[30:31]
	s_cbranch_scc0 .LBB0_317
	s_and_b64 vcc, exec, s[16:17]
	s_cbranch_vccz .LBB0_320
	s_barrier

; #define PG8_WAIT_V(n) asm volatile("s_waitcnt vmcnt(" #n ")" ::: "memory")
; #define PG8_WAIT_L(n) asm volatile("s_waitcnt lgkmcnt(" #n ")" ::: "memory")
; #define PG8_BAR __builtin_amdgcn_s_barrier()
; #define PG8_SCHED __builtin_amdgcn_sched_barrier(0)
;     ...
;             const char* a1 = cA + (size_t)(t + 1) * kstep;
;             const char* a2 = last ? nA : cA + (size_t)(t + 2) * kstep; const char* b2 = last ? nB : cB + (size_t)(t + 2) * kstep;
;             const char* a3 = a2 + kstep; const char* b3 = b2 + kstep;
;             if (last && has_next) S.a_ready(nxt);
;             if constexpr (SP2) {
;             PG8_LDB(B0, 0, 0); PG8_LDB(B1, 0, 1); PG8_SCHED; PG8_LDA(At, 0, 0); PG8_STAGE(PG8_SA(1, 1), a1 + hstepA, voffA);
;             PG8_WAIT_V(8); PG8_WAIT_L(0); PG8_BAR; PG8_MMA(0, 0, At, B0); PG8_MMA(0, 1, At, B1); PG8_BAR; PG8_SCHED;
;             if constexpr (!HALFU) PG8_LDA(At, 0, 1); PG8_STAGE(PG8_SB(0, 0), b2, voffB); PG8_STAGE(PG8_SB(0, 1), b2 + hstep, voffB); PG8_STAGE(PG8_SA(0, 0), a2, voffA);
;             PG8_WAIT_V(8); PG8_WAIT_L(0); PG8_BAR; if constexpr (!HALFU) { PG8_MMA(1, 0, At, B0); PG8_MMA(1, 1, At, B1); } PG8_BAR; PG8_SCHED;
.LBB0_542:
	s_add_u32 s98, s28, 0x80
	s_addc_u32 s99, s29, 0
	s_mov_b32 m0, s53
	s_nop 0
	global_load_lds_dwordx4 v128, s[98:99]
	s_mov_b32 m0, s54
	s_nop 0
	global_load_lds_dwordx4 v130, s[98:99]
	ds_read_b128 v[142:145], v137
	ds_read_b128 v[146:149], v137 offset:1024
	ds_read_b128 v[150:153], v137 offset:2048
	ds_read_b128 v[154:157], v137 offset:3072
	ds_read_b128 v[158:161], v138
	ds_read_b128 v[162:165], v138 offset:1024
	ds_read_b128 v[166:169], v138 offset:2048
	ds_read_b128 v[170:173], v138 offset:3072
	s_add_u32 s30, s28, 0x100
	s_addc_u32 s31, s29, 0
	s_cmp_eq_u32 s61, 12
	s_cselect_b32 s40, s57, s30
	s_cselect_b32 s41, s23, s31
	s_cselect_b32 s38, s58, s59
	s_cselect_b32 s39, s21, s60
	s_add_u32 s36, s40, 0x80
	s_addc_u32 s37, s41, 0
	s_add_u32 s28, s28, 0x40080
	s_addc_u32 s29, s29, 0
	s_add_i32 m0, s45, 0xc000
	ds_read_b128 v[174:177], v139
	ds_read_b128 v[178:181], v139 offset:1024
	ds_read_b128 v[182:185], v139 offset:2048
	ds_read_b128 v[186:189], v139 offset:3072
	ds_read_b128 v[190:193], v139 offset:4096
	ds_read_b128 v[194:197], v139 offset:5120
	ds_read_b128 v[198:201], v139 offset:6144
	ds_read_b128 v[202:205], v139 offset:7168
	global_load_lds_dwordx4 v128, s[28:29]
	s_add_i32 m0, s45, 0xe000
	s_nop 0
	global_load_lds_dwordx4 v130, s[28:29]
	s_waitcnt vmcnt(8) lgkmcnt(0)
	s_barrier
	v_mfma_scale_f32_16x16x128_f8f6f4 v[124:127], v[142:149], v[174:181], v[124:127], v140, v140 op_sel_hi:[0,0,0]
	v_mfma_scale_f32_16x16x128_f8f6f4 v[120:123], v[150:157], v[174:181], v[120:123], v140, v140 op_sel_hi:[0,0,0]
	v_mfma_scale_f32_16x16x128_f8f6f4 v[108:111], v[142:149], v[182:189], v[108:111], v140, v140 op_sel_hi:[0,0,0]
	v_mfma_scale_f32_16x16x128_f8f6f4 v[104:107], v[150:157], v[182:189], v[104:107], v140, v140 op_sel_hi:[0,0,0]
	v_mfma_scale_f32_16x16x128_f8f6f4 v[96:99], v[142:149], v[190:197], v[96:99], v140, v140 op_sel_hi:[0,0,0]
	v_mfma_scale_f32_16x16x128_f8f6f4 v[206:209], v[150:157], v[190:197], v[88:91], v140, v140 op_sel_hi:[0,0,0]
	v_mfma_scale_f32_16x16x128_f8f6f4 v[210:213], v[142:149], v[198:205], v[80:83], v140, v140 op_sel_hi:[0,0,0]
	v_mfma_scale_f32_16x16x128_f8f6f4 v[214:217], v[150:157], v[198:205], v[72:75], v140, v140 op_sel_hi:[0,0,0]
	v_mfma_scale_f32_16x16x128_f8f6f4 v[116:119], v[158:165], v[174:181], v[116:119], v140, v140 op_sel_hi:[0,0,0]
	v_mfma_scale_f32_16x16x128_f8f6f4 v[112:115], v[166:173], v[174:181], v[112:115], v140, v140 op_sel_hi:[0,0,0]
	v_mfma_scale_f32_16x16x128_f8f6f4 v[100:103], v[158:165], v[182:189], v[100:103], v140, v140 op_sel_hi:[0,0,0]
	v_mfma_scale_f32_16x16x128_f8f6f4 v[174:177], v[166:173], v[182:189], v[92:95], v140, v140 op_sel_hi:[0,0,0]
	v_mfma_scale_f32_16x16x128_f8f6f4 v[178:181], v[158:165], v[190:197], v[84:87], v140, v140 op_sel_hi:[0,0,0]
	v_mfma_scale_f32_16x16x128_f8f6f4 v[182:185], v[166:173], v[190:197], v[76:79], v140, v140 op_sel_hi:[0,0,0]
	v_mfma_scale_f32_16x16x128_f8f6f4 v[186:189], v[158:165], v[198:205], v[68:71], v140, v140 op_sel_hi:[0,0,0]
	v_mfma_scale_f32_16x16x128_f8f6f4 v[190:193], v[166:173], v[198:205], v[64:67], v140, v140 op_sel_hi:[0,0,0]
	s_barrier
	s_add_i32 s28, s55, s43
	s_mov_b32 m0, s28
	s_nop 1
	ds_read_b128 v[64:67], v139 offset:16384
	ds_read_b128 v[68:71], v139 offset:17408
	ds_read_b128 v[72:75], v139 offset:18432
	ds_read_b128 v[76:79], v139 offset:19456
	ds_read_b128 v[80:83], v139 offset:20480
	ds_read_b128 v[84:87], v139 offset:21504
	ds_read_b128 v[88:91], v139 offset:22528
	ds_read_b128 v[92:95], v139 offset:23552
	global_load_lds_dwordx4 v128, s[38:39]
	s_add_i32 m0, s28, 0x2000
	s_add_u32 s28, s38, 0x40000
	s_addc_u32 s29, s39, 0
	s_add_i32 s62, s56, s43
	global_load_lds_dwordx4 v130, s[38:39]
	s_mov_b32 m0, s62
	s_nop 0
	global_load_lds_dwordx4 v128, s[28:29]
	s_add_i32 m0, s62, 0x2000
	s_nop 0
	global_load_lds_dwordx4 v130, s[28:29]
	s_waitcnt vmcnt(4) lgkmcnt(0)
	s_barrier
	v_mfma_scale_f32_16x16x128_f8f6f4 v[60:63], v[142:149], v[64:71], v[60:63], v140, v140 op_sel_hi:[0,0,0]
	v_mfma_scale_f32_16x16x128_f8f6f4 v[56:59], v[150:157], v[64:71], v[56:59], v140, v140 op_sel_hi:[0,0,0]
	v_mfma_scale_f32_16x16x128_f8f6f4 v[48:51], v[142:149], v[72:79], v[48:51], v140, v140 op_sel_hi:[0,0,0]
	v_mfma_scale_f32_16x16x128_f8f6f4 v[194:197], v[150:157], v[72:79], v[40:43], v140, v140 op_sel_hi:[0,0,0]
	v_mfma_scale_f32_16x16x128_f8f6f4 v[198:201], v[142:149], v[80:87], v[32:35], v140, v140 op_sel_hi:[0,0,0]
	v_mfma_scale_f32_16x16x128_f8f6f4 v[202:205], v[150:157], v[80:87], v[24:27], v140, v140 op_sel_hi:[0,0,0]
	v_mfma_scale_f32_16x16x128_f8f6f4 v[218:221], v[142:149], v[88:95], v[16:19], v140, v140 op_sel_hi:[0,0,0]
	v_mfma_scale_f32_16x16x128_f8f6f4 v[222:225], v[150:157], v[88:95], v[8:11], v140, v140 op_sel_hi:[0,0,0]
	v_mfma_scale_f32_16x16x128_f8f6f4 v[52:55], v[158:165], v[64:71], v[52:55], v140, v140 op_sel_hi:[0,0,0]
	v_mfma_scale_f32_16x16x128_f8f6f4 v[226:229], v[166:173], v[64:71], v[44:47], v140, v140 op_sel_hi:[0,0,0]
	v_mfma_scale_f32_16x16x128_f8f6f4 v[230:233], v[158:165], v[72:79], v[36:39], v140, v140 op_sel_hi:[0,0,0]
	v_mfma_scale_f32_16x16x128_f8f6f4 v[234:237], v[166:173], v[72:79], v[28:31], v140, v140 op_sel_hi:[0,0,0]
	v_mfma_scale_f32_16x16x128_f8f6f4 v[238:241], v[158:165], v[80:87], v[20:23], v140, v140 op_sel_hi:[0,0,0]
	v_mfma_scale_f32_16x16x128_f8f6f4 v[242:245], v[166:173], v[80:87], v[12:15], v140, v140 op_sel_hi:[0,0,0]
	v_mfma_scale_f32_16x16x128_f8f6f4 v[246:249], v[158:165], v[88:95], v[4:7], v140, v140 op_sel_hi:[0,0,0]
	v_mfma_scale_f32_16x16x128_f8f6f4 v[250:253], v[166:173], v[88:95], v[0:3], v140, v140 op_sel_hi:[0,0,0]
	s_barrier
; #define PG8_WAIT_V(n) asm volatile("s_waitcnt vmcnt(" #n ")" ::: "memory")
; #define PG8_WAIT_L(n) asm volatile("s_waitcnt lgkmcnt(" #n ")" ::: "memory")
; #define PG8_BAR __builtin_amdgcn_s_barrier()
; #define PG8_SCHED __builtin_amdgcn_sched_barrier(0)
;     ...
;         for (int t = 0; t < nt; t += 2) {
;     ...
;             PG8_LDB(B0, 1, 0); PG8_LDB(B1, 1, 1); PG8_SCHED; PG8_LDA(At, 1, 0); PG8_STAGE(PG8_SA(0, 1), a2 + hstepA, voffA);
;             PG8_WAIT_V(8); PG8_WAIT_L(0); PG8_BAR; PG8_MMA(0, 0, At, B0); PG8_MMA(0, 1, At, B1); PG8_BAR; PG8_SCHED;
;             if constexpr (!HALFU) PG8_LDA(At, 1, 1); PG8_STAGE(PG8_SB(1, 0), b3, voffB); PG8_STAGE(PG8_SB(1, 1), b3 + hstep, voffB); PG8_STAGE(PG8_SA(1, 0), a3, voffA);
;             PG8_WAIT_V(8); PG8_WAIT_L(0); PG8_BAR; if constexpr (!HALFU) { PG8_MMA(1, 0, At, B0); PG8_MMA(1, 1, At, B1); } PG8_BAR; PG8_SCHED;
	s_mov_b32 m0, s45
	s_nop 0
	global_load_lds_dwordx4 v128, s[40:41]
	s_mov_b32 m0, s46
	s_nop 0
	global_load_lds_dwordx4 v130, s[40:41]
	s_add_i32 s62, 0, 0x18000
	s_add_i32 s63, 0, 0x1c000
	s_nop 0
	v_add_u32_e32 v12, s62, v136
	v_add_u32_e32 v16, s63, v136
	ds_read_b128 v[0:3], v12
	ds_read_b128 v[4:7], v12 offset:1024
	ds_read_b128 v[8:11], v12 offset:2048
	ds_read_b128 v[12:15], v12 offset:3072
	ds_read_b128 v[142:145], v16
	ds_read_b128 v[146:149], v16 offset:1024
	ds_read_b128 v[150:153], v16 offset:2048
	ds_read_b128 v[154:157], v16 offset:3072
	s_add_u32 s28, s40, 0x40000
	s_addc_u32 s29, s41, 0
	s_mov_b32 m0, s47
	ds_read_b128 v[16:19], v139 offset:32768
	ds_read_b128 v[20:23], v139 offset:33792
	ds_read_b128 v[24:27], v139 offset:34816
	ds_read_b128 v[28:31], v139 offset:35840
	ds_read_b128 v[32:35], v139 offset:36864
	ds_read_b128 v[36:39], v139 offset:37888
	ds_read_b128 v[40:43], v139 offset:38912
	ds_read_b128 v[44:47], v139 offset:39936
	global_load_lds_dwordx4 v128, s[28:29]
	s_mov_b32 m0, s48
	s_nop 0
	global_load_lds_dwordx4 v130, s[28:29]
	s_waitcnt vmcnt(8) lgkmcnt(0)
	s_barrier
	v_mfma_scale_f32_16x16x128_f8f6f4 v[124:127], v[0:7], v[16:23], v[124:127], v140, v140 op_sel_hi:[0,0,0]
	v_mfma_scale_f32_16x16x128_f8f6f4 v[120:123], v[8:15], v[16:23], v[120:123], v140, v140 op_sel_hi:[0,0,0]
	v_mfma_scale_f32_16x16x128_f8f6f4 v[108:111], v[0:7], v[24:31], v[108:111], v140, v140 op_sel_hi:[0,0,0]
	v_mfma_scale_f32_16x16x128_f8f6f4 v[104:107], v[8:15], v[24:31], v[104:107], v140, v140 op_sel_hi:[0,0,0]
	v_mfma_scale_f32_16x16x128_f8f6f4 v[96:99], v[0:7], v[32:39], v[96:99], v140, v140 op_sel_hi:[0,0,0]
	v_mfma_scale_f32_16x16x128_f8f6f4 v[88:91], v[8:15], v[32:39], v[206:209], v140, v140 op_sel_hi:[0,0,0]
	v_mfma_scale_f32_16x16x128_f8f6f4 v[80:83], v[0:7], v[40:47], v[210:213], v140, v140 op_sel_hi:[0,0,0]
	v_mfma_scale_f32_16x16x128_f8f6f4 v[72:75], v[8:15], v[40:47], v[214:217], v140, v140 op_sel_hi:[0,0,0]
	v_mfma_scale_f32_16x16x128_f8f6f4 v[116:119], v[142:149], v[16:23], v[116:119], v140, v140 op_sel_hi:[0,0,0]
	v_mfma_scale_f32_16x16x128_f8f6f4 v[112:115], v[150:157], v[16:23], v[112:115], v140, v140 op_sel_hi:[0,0,0]
	v_mfma_scale_f32_16x16x128_f8f6f4 v[100:103], v[142:149], v[24:31], v[100:103], v140, v140 op_sel_hi:[0,0,0]
	v_mfma_scale_f32_16x16x128_f8f6f4 v[92:95], v[150:157], v[24:31], v[174:177], v140, v140 op_sel_hi:[0,0,0]
	v_mfma_scale_f32_16x16x128_f8f6f4 v[84:87], v[142:149], v[32:39], v[178:181], v140, v140 op_sel_hi:[0,0,0]
	v_mfma_scale_f32_16x16x128_f8f6f4 v[76:79], v[150:157], v[32:39], v[182:185], v140, v140 op_sel_hi:[0,0,0]
	v_mfma_scale_f32_16x16x128_f8f6f4 v[68:71], v[142:149], v[40:47], v[186:189], v140, v140 op_sel_hi:[0,0,0]
	v_mfma_scale_f32_16x16x128_f8f6f4 v[64:67], v[150:157], v[40:47], v[190:193], v140, v140 op_sel_hi:[0,0,0]
	s_barrier
	s_add_u32 s28, s38, 0x80
	s_addc_u32 s29, s39, 0
	s_add_i32 s40, s62, s43
	s_mov_b32 m0, s40
	ds_read_b128 v[158:161], v139 offset:49152
	ds_read_b128 v[162:165], v139 offset:50176
	ds_read_b128 v[166:169], v139 offset:51200
	ds_read_b128 v[170:173], v139 offset:52224
	ds_read_b128 v[174:177], v139 offset:53248
	ds_read_b128 v[178:181], v139 offset:54272
	ds_read_b128 v[182:185], v139 offset:55296
	ds_read_b128 v[186:189], v139 offset:56320
	global_load_lds_dwordx4 v128, s[28:29]
	s_add_i32 m0, s40, 0x2000
	v_lshl_add_u64 v[16:17], s[28:29], 0, v[130:131]
	s_add_u32 s28, s38, 0x40080
	s_addc_u32 s29, s39, 0
	s_add_i32 s38, s63, s43
	global_load_lds_dwordx4 v[16:17], off
	s_mov_b32 m0, s38
	s_nop 0
	global_load_lds_dwordx4 v128, s[28:29]
	s_add_i32 m0, s38, 0x2000
	s_nop 0
	global_load_lds_dwordx4 v130, s[28:29]
	s_waitcnt vmcnt(4) lgkmcnt(0)
	s_barrier
	v_mfma_scale_f32_16x16x128_f8f6f4 v[60:63], v[0:7], v[158:165], v[60:63], v140, v140 op_sel_hi:[0,0,0]
	v_mfma_scale_f32_16x16x128_f8f6f4 v[56:59], v[8:15], v[158:165], v[56:59], v140, v140 op_sel_hi:[0,0,0]
	v_mfma_scale_f32_16x16x128_f8f6f4 v[48:51], v[0:7], v[166:173], v[48:51], v140, v140 op_sel_hi:[0,0,0]
	v_mfma_scale_f32_16x16x128_f8f6f4 v[40:43], v[8:15], v[166:173], v[194:197], v140, v140 op_sel_hi:[0,0,0]
	v_mfma_scale_f32_16x16x128_f8f6f4 v[32:35], v[0:7], v[174:181], v[198:201], v140, v140 op_sel_hi:[0,0,0]
	v_mfma_scale_f32_16x16x128_f8f6f4 v[24:27], v[8:15], v[174:181], v[202:205], v140, v140 op_sel_hi:[0,0,0]
	v_mfma_scale_f32_16x16x128_f8f6f4 v[16:19], v[0:7], v[182:189], v[218:221], v140, v140 op_sel_hi:[0,0,0]
	v_mfma_scale_f32_16x16x128_f8f6f4 v[8:11], v[8:15], v[182:189], v[222:225], v140, v140 op_sel_hi:[0,0,0]
	v_mfma_scale_f32_16x16x128_f8f6f4 v[52:55], v[142:149], v[158:165], v[52:55], v140, v140 op_sel_hi:[0,0,0]
	v_mfma_scale_f32_16x16x128_f8f6f4 v[44:47], v[150:157], v[158:165], v[226:229], v140, v140 op_sel_hi:[0,0,0]
	v_mfma_scale_f32_16x16x128_f8f6f4 v[36:39], v[142:149], v[166:173], v[230:233], v140, v140 op_sel_hi:[0,0,0]
	v_mfma_scale_f32_16x16x128_f8f6f4 v[28:31], v[150:157], v[166:173], v[234:237], v140, v140 op_sel_hi:[0,0,0]
	v_mfma_scale_f32_16x16x128_f8f6f4 v[20:23], v[142:149], v[174:181], v[238:241], v140, v140 op_sel_hi:[0,0,0]
	v_mfma_scale_f32_16x16x128_f8f6f4 v[12:15], v[150:157], v[174:181], v[242:245], v140, v140 op_sel_hi:[0,0,0]
	v_mfma_scale_f32_16x16x128_f8f6f4 v[4:7], v[142:149], v[182:189], v[246:249], v140, v140 op_sel_hi:[0,0,0]
	v_mfma_scale_f32_16x16x128_f8f6f4 v[0:3], v[150:157], v[182:189], v[250:253], v140, v140 op_sel_hi:[0,0,0]
	s_barrier
	s_add_i32 s61, s61, 2
	s_add_u32 s59, s59, 0x100
	s_addc_u32 s60, s60, 0
	s_cmp_gt_u32 s61, 13
	s_mov_b64 s[28:29], s[30:31]
	s_cbranch_scc0 .LBB0_542
	s_and_b64 vcc, exec, s[6:7]
	s_cbranch_vccz .LBB0_545
	s_barrier

; #define PG8_WAIT_V(n) asm volatile("s_waitcnt vmcnt(" #n ")" ::: "memory")
; #define PG8_WAIT_L(n) asm volatile("s_waitcnt lgkmcnt(" #n ")" ::: "memory")
; #define PG8_BAR __builtin_amdgcn_s_barrier()
; #define PG8_SCHED __builtin_amdgcn_sched_barrier(0)
;     ...
;             const char* a1 = cA + (size_t)(t + 1) * kstep;
;             const char* a2 = last ? nA : cA + (size_t)(t + 2) * kstep; const char* b2 = last ? nB : cB + (size_t)(t + 2) * kstep;
;             const char* a3 = a2 + kstep; const char* b3 = b2 + kstep;
;             if (last && has_next) S.a_ready(nxt);
;             if constexpr (SP2) {
;             PG8_LDB(B0, 0, 0); PG8_LDB(B1, 0, 1); PG8_SCHED; PG8_LDA(At, 0, 0); PG8_STAGE(PG8_SA(1, 1), a1 + hstepA, voffA);
;             PG8_WAIT_V(8); PG8_WAIT_L(0); PG8_BAR; PG8_MMA(0, 0, At, B0); PG8_MMA(0, 1, At, B1); PG8_BAR; PG8_SCHED;
;             if constexpr (!HALFU) PG8_LDA(At, 0, 1); PG8_STAGE(PG8_SB(0, 0), b2, voffB); PG8_STAGE(PG8_SB(0, 1), b2 + hstep, voffB); PG8_STAGE(PG8_SA(0, 0), a2, voffA);
;             PG8_WAIT_V(8); PG8_WAIT_L(0); PG8_BAR; if constexpr (!HALFU) { PG8_MMA(1, 0, At, B0); PG8_MMA(1, 1, At, B1); } PG8_BAR; PG8_SCHED;
.LBB0_670:
	s_add_u32 s98, s18, 0x80
	s_addc_u32 s99, s19, 0
	s_mov_b32 m0, s43
	s_nop 0
	global_load_lds_dwordx4 v134, s[98:99]
	s_mov_b32 m0, s44
	s_nop 0
	global_load_lds_dwordx4 v132, s[98:99]
	ds_read_b128 v[144:147], v141
	ds_read_b128 v[148:151], v141 offset:1024
	ds_read_b128 v[152:155], v141 offset:2048
	ds_read_b128 v[156:159], v141 offset:3072
	ds_read_b128 v[160:163], v142
	ds_read_b128 v[164:167], v142 offset:1024
	ds_read_b128 v[168:171], v142 offset:2048
	ds_read_b128 v[172:175], v142 offset:3072
	s_add_u32 s20, s18, 0x100
	s_addc_u32 s21, s19, 0
	s_cmp_eq_u32 s53, 60
	s_cselect_b32 s26, s49, s20
	s_cselect_b32 s27, s11, s21
	s_cselect_b32 s24, s50, s51
	s_cselect_b32 s25, s9, s52
	s_add_u32 s22, s26, 0x80
	s_addc_u32 s23, s27, 0
	s_add_u32 s18, s18, 0x100080
	s_addc_u32 s19, s19, 0
	s_add_i32 m0, s17, 0xc000
	ds_read_b128 v[176:179], v143
	ds_read_b128 v[180:183], v143 offset:1024
	ds_read_b128 v[184:187], v143 offset:2048
	ds_read_b128 v[188:191], v143 offset:3072
	ds_read_b128 v[192:195], v143 offset:4096
	ds_read_b128 v[196:199], v143 offset:5120
	ds_read_b128 v[200:203], v143 offset:6144
	ds_read_b128 v[204:207], v143 offset:7168
	global_load_lds_dwordx4 v134, s[18:19]
	s_add_i32 m0, s17, 0xe000
	s_nop 0
	global_load_lds_dwordx4 v132, s[18:19]
	s_waitcnt vmcnt(8) lgkmcnt(0)
	s_barrier
	v_mfma_f32_16x16x32_bf16 v[124:127], v[144:147], v[176:179], v[124:127]
	v_mfma_f32_16x16x32_bf16 v[120:123], v[152:155], v[176:179], v[120:123]
	v_mfma_f32_16x16x32_bf16 v[108:111], v[144:147], v[184:187], v[108:111]
	v_mfma_f32_16x16x32_bf16 v[104:107], v[152:155], v[184:187], v[104:107]
	v_mfma_f32_16x16x32_bf16 v[92:95], v[144:147], v[192:195], v[92:95]
	v_mfma_f32_16x16x32_bf16 v[88:91], v[152:155], v[192:195], v[88:91]
	v_mfma_f32_16x16x32_bf16 v[76:79], v[144:147], v[200:203], v[76:79]
	v_mfma_f32_16x16x32_bf16 v[72:75], v[152:155], v[200:203], v[72:75]
	v_mfma_f32_16x16x32_bf16 v[124:127], v[148:151], v[180:183], v[124:127]
	v_mfma_f32_16x16x32_bf16 v[120:123], v[156:159], v[180:183], v[120:123]
	v_mfma_f32_16x16x32_bf16 v[108:111], v[148:151], v[188:191], v[108:111]
	v_mfma_f32_16x16x32_bf16 v[104:107], v[156:159], v[188:191], v[104:107]
	v_mfma_f32_16x16x32_bf16 v[92:95], v[148:151], v[196:199], v[92:95]
	v_mfma_f32_16x16x32_bf16 v[88:91], v[156:159], v[196:199], v[88:91]
	v_mfma_f32_16x16x32_bf16 v[76:79], v[148:151], v[204:207], v[76:79]
	v_mfma_f32_16x16x32_bf16 v[72:75], v[156:159], v[204:207], v[72:75]
	v_mfma_f32_16x16x32_bf16 v[116:119], v[160:163], v[176:179], v[116:119]
	v_mfma_f32_16x16x32_bf16 v[112:115], v[168:171], v[176:179], v[112:115]
	v_mfma_f32_16x16x32_bf16 v[100:103], v[160:163], v[184:187], v[100:103]
	v_mfma_f32_16x16x32_bf16 v[96:99], v[168:171], v[184:187], v[96:99]
	v_mfma_f32_16x16x32_bf16 v[84:87], v[160:163], v[192:195], v[84:87]
	v_mfma_f32_16x16x32_bf16 v[80:83], v[168:171], v[192:195], v[80:83]
	v_mfma_f32_16x16x32_bf16 v[68:71], v[160:163], v[200:203], v[68:71]
	v_mfma_f32_16x16x32_bf16 v[64:67], v[168:171], v[200:203], v[64:67]
	v_mfma_f32_16x16x32_bf16 v[116:119], v[164:167], v[180:183], v[116:119]
	v_mfma_f32_16x16x32_bf16 v[112:115], v[172:175], v[180:183], v[112:115]
	v_mfma_f32_16x16x32_bf16 v[100:103], v[164:167], v[188:191], v[100:103]
	v_mfma_f32_16x16x32_bf16 v[96:99], v[172:175], v[188:191], v[96:99]
	v_mfma_f32_16x16x32_bf16 v[84:87], v[164:167], v[196:199], v[84:87]
	v_mfma_f32_16x16x32_bf16 v[80:83], v[172:175], v[196:199], v[80:83]
	v_mfma_f32_16x16x32_bf16 v[68:71], v[164:167], v[204:207], v[68:71]
	v_mfma_f32_16x16x32_bf16 v[64:67], v[172:175], v[204:207], v[64:67]
	s_barrier
	s_add_i32 s18, s45, s30
	s_mov_b32 m0, s18
	ds_read_b128 v[176:179], v143 offset:16384
	ds_read_b128 v[180:183], v143 offset:17408
	ds_read_b128 v[184:187], v143 offset:18432
	ds_read_b128 v[188:191], v143 offset:19456
	ds_read_b128 v[192:195], v143 offset:20480
	ds_read_b128 v[196:199], v143 offset:21504
	ds_read_b128 v[200:203], v143 offset:22528
	ds_read_b128 v[204:207], v143 offset:23552
	global_load_lds_dwordx4 v128, s[24:25]
	s_add_i32 m0, s18, 0x2000
	s_add_u32 s18, s24, 0x100000
	s_addc_u32 s19, s25, 0
	s_add_i32 s54, s46, s30
	global_load_lds_dwordx4 v130, s[24:25]
	s_mov_b32 m0, s54
	s_nop 0
	global_load_lds_dwordx4 v128, s[18:19]
	s_add_i32 m0, s54, 0x2000
	s_nop 0
	global_load_lds_dwordx4 v130, s[18:19]
	s_waitcnt vmcnt(4) lgkmcnt(0)
	s_barrier
	v_mfma_f32_16x16x32_bf16 v[60:63], v[144:147], v[176:179], v[60:63]
	v_mfma_f32_16x16x32_bf16 v[56:59], v[152:155], v[176:179], v[56:59]
	v_mfma_f32_16x16x32_bf16 v[44:47], v[144:147], v[184:187], v[44:47]
	v_mfma_f32_16x16x32_bf16 v[40:43], v[152:155], v[184:187], v[40:43]
	v_mfma_f32_16x16x32_bf16 v[28:31], v[144:147], v[192:195], v[28:31]
	v_mfma_f32_16x16x32_bf16 v[24:27], v[152:155], v[192:195], v[24:27]
	v_mfma_f32_16x16x32_bf16 v[12:15], v[144:147], v[200:203], v[12:15]
	v_mfma_f32_16x16x32_bf16 v[8:11], v[152:155], v[200:203], v[8:11]
	v_mfma_f32_16x16x32_bf16 v[60:63], v[148:151], v[180:183], v[60:63]
	v_mfma_f32_16x16x32_bf16 v[56:59], v[156:159], v[180:183], v[56:59]
	v_mfma_f32_16x16x32_bf16 v[44:47], v[148:151], v[188:191], v[44:47]
	v_mfma_f32_16x16x32_bf16 v[40:43], v[156:159], v[188:191], v[40:43]
	v_mfma_f32_16x16x32_bf16 v[28:31], v[148:151], v[196:199], v[28:31]
	v_mfma_f32_16x16x32_bf16 v[24:27], v[156:159], v[196:199], v[24:27]
	v_mfma_f32_16x16x32_bf16 v[12:15], v[148:151], v[204:207], v[12:15]
	v_mfma_f32_16x16x32_bf16 v[8:11], v[156:159], v[204:207], v[8:11]
	v_mfma_f32_16x16x32_bf16 v[52:55], v[160:163], v[176:179], v[52:55]
	v_mfma_f32_16x16x32_bf16 v[48:51], v[168:171], v[176:179], v[48:51]
	v_mfma_f32_16x16x32_bf16 v[36:39], v[160:163], v[184:187], v[36:39]
	v_mfma_f32_16x16x32_bf16 v[32:35], v[168:171], v[184:187], v[32:35]
	v_mfma_f32_16x16x32_bf16 v[20:23], v[160:163], v[192:195], v[20:23]
	v_mfma_f32_16x16x32_bf16 v[16:19], v[168:171], v[192:195], v[16:19]
	v_mfma_f32_16x16x32_bf16 v[4:7], v[160:163], v[200:203], v[4:7]
	v_mfma_f32_16x16x32_bf16 v[0:3], v[168:171], v[200:203], v[0:3]
	v_mfma_f32_16x16x32_bf16 v[52:55], v[164:167], v[180:183], v[52:55]
	v_mfma_f32_16x16x32_bf16 v[48:51], v[172:175], v[180:183], v[48:51]
	v_mfma_f32_16x16x32_bf16 v[36:39], v[164:167], v[188:191], v[36:39]
	v_mfma_f32_16x16x32_bf16 v[32:35], v[172:175], v[188:191], v[32:35]
	v_mfma_f32_16x16x32_bf16 v[20:23], v[164:167], v[196:199], v[20:23]
	v_mfma_f32_16x16x32_bf16 v[16:19], v[172:175], v[196:199], v[16:19]
	v_mfma_f32_16x16x32_bf16 v[4:7], v[164:167], v[204:207], v[4:7]
	v_mfma_f32_16x16x32_bf16 v[0:3], v[172:175], v[204:207], v[0:3]
	s_barrier
; #define PG8_WAIT_V(n) asm volatile("s_waitcnt vmcnt(" #n ")" ::: "memory")
; #define PG8_WAIT_L(n) asm volatile("s_waitcnt lgkmcnt(" #n ")" ::: "memory")
; #define PG8_BAR __builtin_amdgcn_s_barrier()
; #define PG8_SCHED __builtin_amdgcn_sched_barrier(0)
;     ...
;         for (int t = 0; t < nt; t += 2) {
;     ...
;             PG8_LDB(B0, 1, 0); PG8_LDB(B1, 1, 1); PG8_SCHED; PG8_LDA(At, 1, 0); PG8_STAGE(PG8_SA(0, 1), a2 + hstepA, voffA);
;             PG8_WAIT_V(8); PG8_WAIT_L(0); PG8_BAR; PG8_MMA(0, 0, At, B0); PG8_MMA(0, 1, At, B1); PG8_BAR; PG8_SCHED;
;             if constexpr (!HALFU) PG8_LDA(At, 1, 1); PG8_STAGE(PG8_SB(1, 0), b3, voffB); PG8_STAGE(PG8_SB(1, 1), b3 + hstep, voffB); PG8_STAGE(PG8_SA(1, 0), a3, voffA);
;             PG8_WAIT_V(8); PG8_WAIT_L(0); PG8_BAR; if constexpr (!HALFU) { PG8_MMA(1, 0, At, B0); PG8_MMA(1, 1, At, B1); } PG8_BAR; PG8_SCHED;
	s_mov_b32 m0, s17
	s_nop 0
	global_load_lds_dwordx4 v134, s[26:27]
	s_mov_b32 m0, s36
	s_nop 0
	global_load_lds_dwordx4 v132, s[26:27]
	s_add_i32 s54, 0, 0x18000
	s_add_i32 s55, 0, 0x1c000
	v_add_u32_e32 v156, s54, v140
	v_add_u32_e32 v172, s55, v140
	ds_read_b128 v[144:147], v156
	ds_read_b128 v[148:151], v156 offset:1024
	ds_read_b128 v[152:155], v156 offset:2048
	ds_read_b128 v[156:159], v156 offset:3072
	ds_read_b128 v[160:163], v172
	ds_read_b128 v[164:167], v172 offset:1024
	ds_read_b128 v[168:171], v172 offset:2048
	ds_read_b128 v[172:175], v172 offset:3072
	s_add_u32 s18, s26, 0x100000
	s_addc_u32 s19, s27, 0
	s_mov_b32 m0, s37
	ds_read_b128 v[176:179], v143 offset:32768
	ds_read_b128 v[180:183], v143 offset:33792
	ds_read_b128 v[184:187], v143 offset:34816
	ds_read_b128 v[188:191], v143 offset:35840
	ds_read_b128 v[192:195], v143 offset:36864
	ds_read_b128 v[196:199], v143 offset:37888
	ds_read_b128 v[200:203], v143 offset:38912
	ds_read_b128 v[204:207], v143 offset:39936
	global_load_lds_dwordx4 v134, s[18:19]
	s_mov_b32 m0, s38
	s_nop 0
	global_load_lds_dwordx4 v132, s[18:19]
	s_waitcnt vmcnt(8) lgkmcnt(0)
	s_barrier
	v_mfma_f32_16x16x32_bf16 v[124:127], v[144:147], v[176:179], v[124:127]
	v_mfma_f32_16x16x32_bf16 v[120:123], v[152:155], v[176:179], v[120:123]
	v_mfma_f32_16x16x32_bf16 v[108:111], v[144:147], v[184:187], v[108:111]
	v_mfma_f32_16x16x32_bf16 v[104:107], v[152:155], v[184:187], v[104:107]
	v_mfma_f32_16x16x32_bf16 v[92:95], v[144:147], v[192:195], v[92:95]
	v_mfma_f32_16x16x32_bf16 v[88:91], v[152:155], v[192:195], v[88:91]
	v_mfma_f32_16x16x32_bf16 v[76:79], v[144:147], v[200:203], v[76:79]
	v_mfma_f32_16x16x32_bf16 v[72:75], v[152:155], v[200:203], v[72:75]
	v_mfma_f32_16x16x32_bf16 v[124:127], v[148:151], v[180:183], v[124:127]
	v_mfma_f32_16x16x32_bf16 v[120:123], v[156:159], v[180:183], v[120:123]
	v_mfma_f32_16x16x32_bf16 v[108:111], v[148:151], v[188:191], v[108:111]
	v_mfma_f32_16x16x32_bf16 v[104:107], v[156:159], v[188:191], v[104:107]
	v_mfma_f32_16x16x32_bf16 v[92:95], v[148:151], v[196:199], v[92:95]
	v_mfma_f32_16x16x32_bf16 v[88:91], v[156:159], v[196:199], v[88:91]
	v_mfma_f32_16x16x32_bf16 v[76:79], v[148:151], v[204:207], v[76:79]
	v_mfma_f32_16x16x32_bf16 v[72:75], v[156:159], v[204:207], v[72:75]
	v_mfma_f32_16x16x32_bf16 v[116:119], v[160:163], v[176:179], v[116:119]
	v_mfma_f32_16x16x32_bf16 v[112:115], v[168:171], v[176:179], v[112:115]
	v_mfma_f32_16x16x32_bf16 v[100:103], v[160:163], v[184:187], v[100:103]
	v_mfma_f32_16x16x32_bf16 v[96:99], v[168:171], v[184:187], v[96:99]
	v_mfma_f32_16x16x32_bf16 v[84:87], v[160:163], v[192:195], v[84:87]
	v_mfma_f32_16x16x32_bf16 v[80:83], v[168:171], v[192:195], v[80:83]
	v_mfma_f32_16x16x32_bf16 v[68:71], v[160:163], v[200:203], v[68:71]
	v_mfma_f32_16x16x32_bf16 v[64:67], v[168:171], v[200:203], v[64:67]
	v_mfma_f32_16x16x32_bf16 v[116:119], v[164:167], v[180:183], v[116:119]
	v_mfma_f32_16x16x32_bf16 v[112:115], v[172:175], v[180:183], v[112:115]
	v_mfma_f32_16x16x32_bf16 v[100:103], v[164:167], v[188:191], v[100:103]
	v_mfma_f32_16x16x32_bf16 v[96:99], v[172:175], v[188:191], v[96:99]
	v_mfma_f32_16x16x32_bf16 v[84:87], v[164:167], v[196:199], v[84:87]
	v_mfma_f32_16x16x32_bf16 v[80:83], v[172:175], v[196:199], v[80:83]
	v_mfma_f32_16x16x32_bf16 v[68:71], v[164:167], v[204:207], v[68:71]
	v_mfma_f32_16x16x32_bf16 v[64:67], v[172:175], v[204:207], v[64:67]
	s_barrier
	s_add_u32 s18, s24, 0x80
	s_addc_u32 s19, s25, 0
	s_add_i32 s26, s54, s30
	s_mov_b32 m0, s26
	ds_read_b128 v[176:179], v143 offset:49152
	ds_read_b128 v[180:183], v143 offset:50176
	ds_read_b128 v[184:187], v143 offset:51200
	ds_read_b128 v[188:191], v143 offset:52224
	ds_read_b128 v[192:195], v143 offset:53248
	ds_read_b128 v[196:199], v143 offset:54272
	ds_read_b128 v[200:203], v143 offset:55296
	ds_read_b128 v[204:207], v143 offset:56320
	global_load_lds_dwordx4 v128, s[18:19]
	s_add_i32 m0, s26, 0x2000
	v_lshl_add_u64 v[208:209], s[18:19], 0, v[130:131]
	s_add_u32 s18, s24, 0x100080
	s_addc_u32 s19, s25, 0
	s_add_i32 s24, s55, s30
	global_load_lds_dwordx4 v[208:209], off
	s_mov_b32 m0, s24
	s_nop 0
	global_load_lds_dwordx4 v128, s[18:19]
	s_add_i32 m0, s24, 0x2000
	s_nop 0
	global_load_lds_dwordx4 v130, s[18:19]
	s_waitcnt vmcnt(4) lgkmcnt(0)
	s_barrier
	v_mfma_f32_16x16x32_bf16 v[60:63], v[144:147], v[176:179], v[60:63]
	v_mfma_f32_16x16x32_bf16 v[56:59], v[152:155], v[176:179], v[56:59]
	v_mfma_f32_16x16x32_bf16 v[44:47], v[144:147], v[184:187], v[44:47]
	v_mfma_f32_16x16x32_bf16 v[40:43], v[152:155], v[184:187], v[40:43]
	v_mfma_f32_16x16x32_bf16 v[28:31], v[144:147], v[192:195], v[28:31]
	v_mfma_f32_16x16x32_bf16 v[24:27], v[152:155], v[192:195], v[24:27]
	v_mfma_f32_16x16x32_bf16 v[12:15], v[144:147], v[200:203], v[12:15]
	v_mfma_f32_16x16x32_bf16 v[8:11], v[152:155], v[200:203], v[8:11]
	v_mfma_f32_16x16x32_bf16 v[60:63], v[148:151], v[180:183], v[60:63]
	v_mfma_f32_16x16x32_bf16 v[56:59], v[156:159], v[180:183], v[56:59]
	v_mfma_f32_16x16x32_bf16 v[44:47], v[148:151], v[188:191], v[44:47]
	v_mfma_f32_16x16x32_bf16 v[40:43], v[156:159], v[188:191], v[40:43]
	v_mfma_f32_16x16x32_bf16 v[28:31], v[148:151], v[196:199], v[28:31]
	v_mfma_f32_16x16x32_bf16 v[24:27], v[156:159], v[196:199], v[24:27]
	v_mfma_f32_16x16x32_bf16 v[12:15], v[148:151], v[204:207], v[12:15]
	v_mfma_f32_16x16x32_bf16 v[8:11], v[156:159], v[204:207], v[8:11]
	v_mfma_f32_16x16x32_bf16 v[52:55], v[160:163], v[176:179], v[52:55]
	v_mfma_f32_16x16x32_bf16 v[48:51], v[168:171], v[176:179], v[48:51]
	v_mfma_f32_16x16x32_bf16 v[36:39], v[160:163], v[184:187], v[36:39]
	v_mfma_f32_16x16x32_bf16 v[32:35], v[168:171], v[184:187], v[32:35]
	v_mfma_f32_16x16x32_bf16 v[20:23], v[160:163], v[192:195], v[20:23]
	v_mfma_f32_16x16x32_bf16 v[16:19], v[168:171], v[192:195], v[16:19]
	v_mfma_f32_16x16x32_bf16 v[4:7], v[160:163], v[200:203], v[4:7]
	v_mfma_f32_16x16x32_bf16 v[0:3], v[168:171], v[200:203], v[0:3]
	v_mfma_f32_16x16x32_bf16 v[52:55], v[164:167], v[180:183], v[52:55]
	v_mfma_f32_16x16x32_bf16 v[48:51], v[172:175], v[180:183], v[48:51]
	v_mfma_f32_16x16x32_bf16 v[36:39], v[164:167], v[188:191], v[36:39]
	v_mfma_f32_16x16x32_bf16 v[32:35], v[172:175], v[188:191], v[32:35]
	v_mfma_f32_16x16x32_bf16 v[20:23], v[164:167], v[196:199], v[20:23]
	v_mfma_f32_16x16x32_bf16 v[16:19], v[172:175], v[196:199], v[16:19]
	v_mfma_f32_16x16x32_bf16 v[4:7], v[164:167], v[204:207], v[4:7]
	v_mfma_f32_16x16x32_bf16 v[0:3], v[172:175], v[204:207], v[0:3]
	s_barrier
	s_add_i32 s53, s53, 2
	s_add_u32 s51, s51, 0x100
	s_addc_u32 s52, s52, 0
	s_cmp_gt_u32 s53, 61
	s_mov_b64 s[18:19], s[20:21]
	s_cbranch_scc0 .LBB0_670
	s_and_b64 vcc, exec, s[6:7]
	s_cbranch_vccz .LBB0_673
	s_barrier

; #define PG8_WAIT_V(n) asm volatile("s_waitcnt vmcnt(" #n ")" ::: "memory")
; #define PG8_WAIT_L(n) asm volatile("s_waitcnt lgkmcnt(" #n ")" ::: "memory")
; #define PG8_BAR __builtin_amdgcn_s_barrier()
; #define PG8_SCHED __builtin_amdgcn_sched_barrier(0)
;     ...
;             const char* a1 = cA + (size_t)(t + 1) * kstep;
;             const char* a2 = last ? nA : cA + (size_t)(t + 2) * kstep; const char* b2 = last ? nB : cB + (size_t)(t + 2) * kstep;
;             const char* a3 = a2 + kstep; const char* b3 = b2 + kstep;
;             if (last && has_next) S.a_ready(nxt);
;             if constexpr (SP2) {
;             PG8_LDB(B0, 0, 0); PG8_LDB(B1, 0, 1); PG8_SCHED; PG8_LDA(At, 0, 0); PG8_STAGE(PG8_SA(1, 1), a1 + hstepA, voffA);
;             PG8_WAIT_V(8); PG8_WAIT_L(0); PG8_BAR; PG8_MMA(0, 0, At, B0); PG8_MMA(0, 1, At, B1); PG8_BAR; PG8_SCHED;
;             if constexpr (!HALFU) PG8_LDA(At, 0, 1); PG8_STAGE(PG8_SB(0, 0), b2, voffB); PG8_STAGE(PG8_SB(0, 1), b2 + hstep, voffB); PG8_STAGE(PG8_SA(0, 0), a2, voffA);
;             PG8_WAIT_V(8); PG8_WAIT_L(0); PG8_BAR; if constexpr (!HALFU) { PG8_MMA(1, 0, At, B0); PG8_MMA(1, 1, At, B1); } PG8_BAR; PG8_SCHED;
.LBB0_793:
	s_add_u32 s98, s10, 0x80
	s_addc_u32 s99, s11, 0
	s_mov_b32 m0, s43
	s_nop 0
	global_load_lds_dwordx4 v128, s[98:99]
	s_mov_b32 m0, s44
	s_nop 0
	global_load_lds_dwordx4 v130, s[98:99]
	ds_read_b128 v[140:143], v137
	ds_read_b128 v[144:147], v137 offset:1024
	ds_read_b128 v[148:151], v137 offset:2048
	ds_read_b128 v[152:155], v137 offset:3072
	ds_read_b128 v[156:159], v138
	ds_read_b128 v[160:163], v138 offset:1024
	ds_read_b128 v[164:167], v138 offset:2048
	ds_read_b128 v[168:171], v138 offset:3072
	s_add_u32 s22, s10, 0x100
	s_addc_u32 s23, s11, 0
	s_cmpk_eq_i32 s54, 0xa8
	s_cselect_b32 s28, s6, s22
	s_cselect_b32 s29, s7, s23
	s_cselect_b32 s26, s20, s52
	s_cselect_b32 s27, s21, s53
	s_add_u32 s24, s28, 0x80
	s_addc_u32 s25, s29, 0
	s_add_u32 s10, s10, 0x2b0080
	s_addc_u32 s11, s11, 0
	s_add_i32 m0, s36, 0xc000
	ds_read_b128 v[172:175], v139
	ds_read_b128 v[176:179], v139 offset:1024
	ds_read_b128 v[180:183], v139 offset:2048
	ds_read_b128 v[184:187], v139 offset:3072
	ds_read_b128 v[188:191], v139 offset:4096
	ds_read_b128 v[192:195], v139 offset:5120
	ds_read_b128 v[196:199], v139 offset:6144
	ds_read_b128 v[200:203], v139 offset:7168
	global_load_lds_dwordx4 v128, s[10:11]
	s_add_i32 m0, s36, 0xe000
	s_nop 0
	global_load_lds_dwordx4 v130, s[10:11]
	s_waitcnt vmcnt(8) lgkmcnt(0)
	s_barrier
	v_mfma_f32_16x16x32_bf16 v[124:127], v[140:143], v[172:175], v[124:127]
	v_mfma_f32_16x16x32_bf16 v[120:123], v[148:151], v[172:175], v[120:123]
	v_mfma_f32_16x16x32_bf16 v[112:115], v[140:143], v[180:183], v[112:115]
	v_mfma_f32_16x16x32_bf16 v[104:107], v[148:151], v[180:183], v[104:107]
	v_mfma_f32_16x16x32_bf16 v[96:99], v[140:143], v[188:191], v[96:99]
	v_mfma_f32_16x16x32_bf16 v[88:91], v[148:151], v[188:191], v[88:91]
	v_mfma_f32_16x16x32_bf16 v[80:83], v[140:143], v[196:199], v[80:83]
	v_mfma_f32_16x16x32_bf16 v[72:75], v[148:151], v[196:199], v[72:75]
	v_mfma_f32_16x16x32_bf16 v[124:127], v[144:147], v[176:179], v[124:127]
	v_mfma_f32_16x16x32_bf16 v[120:123], v[152:155], v[176:179], v[120:123]
	v_mfma_f32_16x16x32_bf16 v[112:115], v[144:147], v[184:187], v[112:115]
	v_mfma_f32_16x16x32_bf16 v[104:107], v[152:155], v[184:187], v[104:107]
	v_mfma_f32_16x16x32_bf16 v[96:99], v[144:147], v[192:195], v[96:99]
	v_mfma_f32_16x16x32_bf16 v[88:91], v[152:155], v[192:195], v[88:91]
	v_mfma_f32_16x16x32_bf16 v[80:83], v[144:147], v[200:203], v[80:83]
	v_mfma_f32_16x16x32_bf16 v[72:75], v[152:155], v[200:203], v[72:75]
	v_mfma_f32_16x16x32_bf16 v[116:119], v[156:159], v[172:175], v[116:119]
	v_mfma_f32_16x16x32_bf16 v[108:111], v[164:167], v[172:175], v[108:111]
	v_mfma_f32_16x16x32_bf16 v[100:103], v[156:159], v[180:183], v[100:103]
	v_mfma_f32_16x16x32_bf16 v[92:95], v[164:167], v[180:183], v[92:95]
	v_mfma_f32_16x16x32_bf16 v[84:87], v[156:159], v[188:191], v[84:87]
	v_mfma_f32_16x16x32_bf16 v[76:79], v[164:167], v[188:191], v[76:79]
	v_mfma_f32_16x16x32_bf16 v[68:71], v[156:159], v[196:199], v[68:71]
	v_mfma_f32_16x16x32_bf16 v[64:67], v[164:167], v[196:199], v[64:67]
	v_mfma_f32_16x16x32_bf16 v[116:119], v[160:163], v[176:179], v[116:119]
	v_mfma_f32_16x16x32_bf16 v[108:111], v[168:171], v[176:179], v[108:111]
	v_mfma_f32_16x16x32_bf16 v[100:103], v[160:163], v[184:187], v[100:103]
	v_mfma_f32_16x16x32_bf16 v[92:95], v[168:171], v[184:187], v[92:95]
	v_mfma_f32_16x16x32_bf16 v[84:87], v[160:163], v[192:195], v[84:87]
	v_mfma_f32_16x16x32_bf16 v[76:79], v[168:171], v[192:195], v[76:79]
	v_mfma_f32_16x16x32_bf16 v[68:71], v[160:163], v[200:203], v[68:71]
	v_mfma_f32_16x16x32_bf16 v[64:67], v[168:171], v[200:203], v[64:67]
	s_barrier
	s_add_i32 s10, s46, s31
	s_mov_b32 m0, s10
	ds_read_b128 v[172:175], v139 offset:16384
	ds_read_b128 v[176:179], v139 offset:17408
	ds_read_b128 v[180:183], v139 offset:18432
	ds_read_b128 v[184:187], v139 offset:19456
	ds_read_b128 v[188:191], v139 offset:20480
	ds_read_b128 v[192:195], v139 offset:21504
	ds_read_b128 v[196:199], v139 offset:22528
	ds_read_b128 v[200:203], v139 offset:23552
	global_load_lds_dwordx4 v128, s[26:27]
	s_add_i32 m0, s10, 0x2000
	s_add_u32 s10, s26, 0x2b0000
	s_addc_u32 s11, s27, 0
	s_add_i32 s55, s47, s31
	global_load_lds_dwordx4 v130, s[26:27]
	s_mov_b32 m0, s55
	s_nop 0
	global_load_lds_dwordx4 v128, s[10:11]
	s_add_i32 m0, s55, 0x2000
	s_nop 0
	global_load_lds_dwordx4 v130, s[10:11]
	s_waitcnt vmcnt(4) lgkmcnt(0)
	s_barrier
	v_mfma_f32_16x16x32_bf16 v[60:63], v[140:143], v[172:175], v[60:63]
	v_mfma_f32_16x16x32_bf16 v[56:59], v[148:151], v[172:175], v[56:59]
	v_mfma_f32_16x16x32_bf16 v[48:51], v[140:143], v[180:183], v[48:51]
	v_mfma_f32_16x16x32_bf16 v[40:43], v[148:151], v[180:183], v[40:43]
	v_mfma_f32_16x16x32_bf16 v[32:35], v[140:143], v[188:191], v[32:35]
	v_mfma_f32_16x16x32_bf16 v[24:27], v[148:151], v[188:191], v[24:27]
	v_mfma_f32_16x16x32_bf16 v[16:19], v[140:143], v[196:199], v[16:19]
	v_mfma_f32_16x16x32_bf16 v[8:11], v[148:151], v[196:199], v[8:11]
	v_mfma_f32_16x16x32_bf16 v[60:63], v[144:147], v[176:179], v[60:63]
	v_mfma_f32_16x16x32_bf16 v[56:59], v[152:155], v[176:179], v[56:59]
	v_mfma_f32_16x16x32_bf16 v[48:51], v[144:147], v[184:187], v[48:51]
	v_mfma_f32_16x16x32_bf16 v[40:43], v[152:155], v[184:187], v[40:43]
	v_mfma_f32_16x16x32_bf16 v[32:35], v[144:147], v[192:195], v[32:35]
	v_mfma_f32_16x16x32_bf16 v[24:27], v[152:155], v[192:195], v[24:27]
	v_mfma_f32_16x16x32_bf16 v[16:19], v[144:147], v[200:203], v[16:19]
	v_mfma_f32_16x16x32_bf16 v[8:11], v[152:155], v[200:203], v[8:11]
	v_mfma_f32_16x16x32_bf16 v[52:55], v[156:159], v[172:175], v[52:55]
	v_mfma_f32_16x16x32_bf16 v[44:47], v[164:167], v[172:175], v[44:47]
	v_mfma_f32_16x16x32_bf16 v[36:39], v[156:159], v[180:183], v[36:39]
	v_mfma_f32_16x16x32_bf16 v[28:31], v[164:167], v[180:183], v[28:31]
	v_mfma_f32_16x16x32_bf16 v[20:23], v[156:159], v[188:191], v[20:23]
	v_mfma_f32_16x16x32_bf16 v[12:15], v[164:167], v[188:191], v[12:15]
	v_mfma_f32_16x16x32_bf16 v[4:7], v[156:159], v[196:199], v[4:7]
	v_mfma_f32_16x16x32_bf16 v[0:3], v[164:167], v[196:199], v[0:3]
	v_mfma_f32_16x16x32_bf16 v[52:55], v[160:163], v[176:179], v[52:55]
	v_mfma_f32_16x16x32_bf16 v[44:47], v[168:171], v[176:179], v[44:47]
	v_mfma_f32_16x16x32_bf16 v[36:39], v[160:163], v[184:187], v[36:39]
	v_mfma_f32_16x16x32_bf16 v[28:31], v[168:171], v[184:187], v[28:31]
	v_mfma_f32_16x16x32_bf16 v[20:23], v[160:163], v[192:195], v[20:23]
	v_mfma_f32_16x16x32_bf16 v[12:15], v[168:171], v[192:195], v[12:15]
	v_mfma_f32_16x16x32_bf16 v[4:7], v[160:163], v[200:203], v[4:7]
	v_mfma_f32_16x16x32_bf16 v[0:3], v[168:171], v[200:203], v[0:3]
	s_barrier
; #define PG8_WAIT_V(n) asm volatile("s_waitcnt vmcnt(" #n ")" ::: "memory")
; #define PG8_WAIT_L(n) asm volatile("s_waitcnt lgkmcnt(" #n ")" ::: "memory")
; #define PG8_BAR __builtin_amdgcn_s_barrier()
; #define PG8_SCHED __builtin_amdgcn_sched_barrier(0)
;     ...
;         for (int t = 0; t < nt; t += 2) {
;     ...
;             PG8_LDB(B0, 1, 0); PG8_LDB(B1, 1, 1); PG8_SCHED; PG8_LDA(At, 1, 0); PG8_STAGE(PG8_SA(0, 1), a2 + hstepA, voffA);
;             PG8_WAIT_V(8); PG8_WAIT_L(0); PG8_BAR; PG8_MMA(0, 0, At, B0); PG8_MMA(0, 1, At, B1); PG8_BAR; PG8_SCHED;
;             if constexpr (!HALFU) PG8_LDA(At, 1, 1); PG8_STAGE(PG8_SB(1, 0), b3, voffB); PG8_STAGE(PG8_SB(1, 1), b3 + hstep, voffB); PG8_STAGE(PG8_SA(1, 0), a3, voffA);
;             PG8_WAIT_V(8); PG8_WAIT_L(0); PG8_BAR; if constexpr (!HALFU) { PG8_MMA(1, 0, At, B0); PG8_MMA(1, 1, At, B1); } PG8_BAR; PG8_SCHED;
	s_mov_b32 m0, s36
	s_nop 0
	global_load_lds_dwordx4 v128, s[28:29]
	s_mov_b32 m0, s37
	s_nop 0
	global_load_lds_dwordx4 v130, s[28:29]
	s_add_i32 s55, 0, 0x18000
	s_add_i32 s56, 0, 0x1c000
	v_add_u32_e32 v152, s55, v136
	v_add_u32_e32 v168, s56, v136
	ds_read_b128 v[140:143], v152
	ds_read_b128 v[144:147], v152 offset:1024
	ds_read_b128 v[148:151], v152 offset:2048
	ds_read_b128 v[152:155], v152 offset:3072
	ds_read_b128 v[156:159], v168
	ds_read_b128 v[160:163], v168 offset:1024
	ds_read_b128 v[164:167], v168 offset:2048
	ds_read_b128 v[168:171], v168 offset:3072
	s_add_u32 s10, s28, 0x2b0000
	s_addc_u32 s11, s29, 0
	s_mov_b32 m0, s38
	ds_read_b128 v[172:175], v139 offset:32768
	ds_read_b128 v[176:179], v139 offset:33792
	ds_read_b128 v[180:183], v139 offset:34816
	ds_read_b128 v[184:187], v139 offset:35840
	ds_read_b128 v[188:191], v139 offset:36864
	ds_read_b128 v[192:195], v139 offset:37888
	ds_read_b128 v[196:199], v139 offset:38912
	ds_read_b128 v[200:203], v139 offset:39936
	global_load_lds_dwordx4 v128, s[10:11]
	s_mov_b32 m0, s39
	s_nop 0
	global_load_lds_dwordx4 v130, s[10:11]
	s_waitcnt vmcnt(8) lgkmcnt(0)
	s_barrier
	v_mfma_f32_16x16x32_bf16 v[124:127], v[140:143], v[172:175], v[124:127]
	v_mfma_f32_16x16x32_bf16 v[120:123], v[148:151], v[172:175], v[120:123]
	v_mfma_f32_16x16x32_bf16 v[112:115], v[140:143], v[180:183], v[112:115]
	v_mfma_f32_16x16x32_bf16 v[104:107], v[148:151], v[180:183], v[104:107]
	v_mfma_f32_16x16x32_bf16 v[96:99], v[140:143], v[188:191], v[96:99]
	v_mfma_f32_16x16x32_bf16 v[88:91], v[148:151], v[188:191], v[88:91]
	v_mfma_f32_16x16x32_bf16 v[80:83], v[140:143], v[196:199], v[80:83]
	v_mfma_f32_16x16x32_bf16 v[72:75], v[148:151], v[196:199], v[72:75]
	v_mfma_f32_16x16x32_bf16 v[124:127], v[144:147], v[176:179], v[124:127]
	v_mfma_f32_16x16x32_bf16 v[120:123], v[152:155], v[176:179], v[120:123]
	v_mfma_f32_16x16x32_bf16 v[112:115], v[144:147], v[184:187], v[112:115]
	v_mfma_f32_16x16x32_bf16 v[104:107], v[152:155], v[184:187], v[104:107]
	v_mfma_f32_16x16x32_bf16 v[96:99], v[144:147], v[192:195], v[96:99]
	v_mfma_f32_16x16x32_bf16 v[88:91], v[152:155], v[192:195], v[88:91]
	v_mfma_f32_16x16x32_bf16 v[80:83], v[144:147], v[200:203], v[80:83]
	v_mfma_f32_16x16x32_bf16 v[72:75], v[152:155], v[200:203], v[72:75]
	v_mfma_f32_16x16x32_bf16 v[116:119], v[156:159], v[172:175], v[116:119]
	v_mfma_f32_16x16x32_bf16 v[108:111], v[164:167], v[172:175], v[108:111]
	v_mfma_f32_16x16x32_bf16 v[100:103], v[156:159], v[180:183], v[100:103]
	v_mfma_f32_16x16x32_bf16 v[92:95], v[164:167], v[180:183], v[92:95]
	v_mfma_f32_16x16x32_bf16 v[84:87], v[156:159], v[188:191], v[84:87]
	v_mfma_f32_16x16x32_bf16 v[76:79], v[164:167], v[188:191], v[76:79]
	v_mfma_f32_16x16x32_bf16 v[68:71], v[156:159], v[196:199], v[68:71]
	v_mfma_f32_16x16x32_bf16 v[64:67], v[164:167], v[196:199], v[64:67]
	v_mfma_f32_16x16x32_bf16 v[116:119], v[160:163], v[176:179], v[116:119]
	v_mfma_f32_16x16x32_bf16 v[108:111], v[168:171], v[176:179], v[108:111]
	v_mfma_f32_16x16x32_bf16 v[100:103], v[160:163], v[184:187], v[100:103]
	v_mfma_f32_16x16x32_bf16 v[92:95], v[168:171], v[184:187], v[92:95]
	v_mfma_f32_16x16x32_bf16 v[84:87], v[160:163], v[192:195], v[84:87]
	v_mfma_f32_16x16x32_bf16 v[76:79], v[168:171], v[192:195], v[76:79]
	v_mfma_f32_16x16x32_bf16 v[68:71], v[160:163], v[200:203], v[68:71]
	v_mfma_f32_16x16x32_bf16 v[64:67], v[168:171], v[200:203], v[64:67]
	s_barrier
	s_add_u32 s10, s26, 0x80
	s_addc_u32 s11, s27, 0
	s_add_i32 s28, s55, s31
	s_mov_b32 m0, s28
	ds_read_b128 v[172:175], v139 offset:49152
	ds_read_b128 v[176:179], v139 offset:50176
	ds_read_b128 v[180:183], v139 offset:51200
	ds_read_b128 v[184:187], v139 offset:52224
	ds_read_b128 v[188:191], v139 offset:53248
	ds_read_b128 v[192:195], v139 offset:54272
	ds_read_b128 v[196:199], v139 offset:55296
	ds_read_b128 v[200:203], v139 offset:56320
	global_load_lds_dwordx4 v128, s[10:11]
	s_add_i32 m0, s28, 0x2000
	v_lshl_add_u64 v[204:205], s[10:11], 0, v[130:131]
	s_add_u32 s10, s26, 0x2b0080
	s_addc_u32 s11, s27, 0
	s_add_i32 s26, s56, s31
	global_load_lds_dwordx4 v[204:205], off
	s_mov_b32 m0, s26
	s_nop 0
	global_load_lds_dwordx4 v128, s[10:11]
	s_add_i32 m0, s26, 0x2000
	s_nop 0
	global_load_lds_dwordx4 v130, s[10:11]
	s_waitcnt vmcnt(4) lgkmcnt(0)
	s_barrier
	v_mfma_f32_16x16x32_bf16 v[60:63], v[140:143], v[172:175], v[60:63]
	v_mfma_f32_16x16x32_bf16 v[56:59], v[148:151], v[172:175], v[56:59]
	v_mfma_f32_16x16x32_bf16 v[48:51], v[140:143], v[180:183], v[48:51]
	v_mfma_f32_16x16x32_bf16 v[40:43], v[148:151], v[180:183], v[40:43]
	v_mfma_f32_16x16x32_bf16 v[32:35], v[140:143], v[188:191], v[32:35]
	v_mfma_f32_16x16x32_bf16 v[24:27], v[148:151], v[188:191], v[24:27]
	v_mfma_f32_16x16x32_bf16 v[16:19], v[140:143], v[196:199], v[16:19]
	v_mfma_f32_16x16x32_bf16 v[8:11], v[148:151], v[196:199], v[8:11]
	v_mfma_f32_16x16x32_bf16 v[60:63], v[144:147], v[176:179], v[60:63]
	v_mfma_f32_16x16x32_bf16 v[56:59], v[152:155], v[176:179], v[56:59]
	v_mfma_f32_16x16x32_bf16 v[48:51], v[144:147], v[184:187], v[48:51]
	v_mfma_f32_16x16x32_bf16 v[40:43], v[152:155], v[184:187], v[40:43]
	v_mfma_f32_16x16x32_bf16 v[32:35], v[144:147], v[192:195], v[32:35]
	v_mfma_f32_16x16x32_bf16 v[24:27], v[152:155], v[192:195], v[24:27]
	v_mfma_f32_16x16x32_bf16 v[16:19], v[144:147], v[200:203], v[16:19]
	v_mfma_f32_16x16x32_bf16 v[8:11], v[152:155], v[200:203], v[8:11]
	v_mfma_f32_16x16x32_bf16 v[52:55], v[156:159], v[172:175], v[52:55]
	v_mfma_f32_16x16x32_bf16 v[44:47], v[164:167], v[172:175], v[44:47]
	v_mfma_f32_16x16x32_bf16 v[36:39], v[156:159], v[180:183], v[36:39]
	v_mfma_f32_16x16x32_bf16 v[28:31], v[164:167], v[180:183], v[28:31]
	v_mfma_f32_16x16x32_bf16 v[20:23], v[156:159], v[188:191], v[20:23]
	v_mfma_f32_16x16x32_bf16 v[12:15], v[164:167], v[188:191], v[12:15]
	v_mfma_f32_16x16x32_bf16 v[4:7], v[156:159], v[196:199], v[4:7]
	v_mfma_f32_16x16x32_bf16 v[0:3], v[164:167], v[196:199], v[0:3]
	v_mfma_f32_16x16x32_bf16 v[52:55], v[160:163], v[176:179], v[52:55]
	v_mfma_f32_16x16x32_bf16 v[44:47], v[168:171], v[176:179], v[44:47]
	v_mfma_f32_16x16x32_bf16 v[36:39], v[160:163], v[184:187], v[36:39]
	v_mfma_f32_16x16x32_bf16 v[28:31], v[168:171], v[184:187], v[28:31]
	v_mfma_f32_16x16x32_bf16 v[20:23], v[160:163], v[192:195], v[20:23]
	v_mfma_f32_16x16x32_bf16 v[12:15], v[168:171], v[192:195], v[12:15]
	v_mfma_f32_16x16x32_bf16 v[4:7], v[160:163], v[200:203], v[4:7]
	v_mfma_f32_16x16x32_bf16 v[0:3], v[168:171], v[200:203], v[0:3]
	s_barrier
	s_add_i32 s54, s54, 2
	s_add_u32 s52, s52, 0x100
	s_addc_u32 s53, s53, 0
	s_cmpk_gt_u32 s54, 0xa9
	s_mov_b64 s[10:11], s[22:23]
	s_cbranch_scc0 .LBB0_793
	s_and_b64 vcc, exec, s[12:13]
	s_cbranch_vccz .LBB0_796
	s_barrier

; #define PG8_WAIT_V(n) asm volatile("s_waitcnt vmcnt(" #n ")" ::: "memory")
; #define PG8_WAIT_L(n) asm volatile("s_waitcnt lgkmcnt(" #n ")" ::: "memory")
; #define PG8_BAR __builtin_amdgcn_s_barrier()
; #define PG8_SCHED __builtin_amdgcn_sched_barrier(0)
;     ...
;             const char* a1 = cA + (size_t)(t + 1) * kstep;
;             const char* a2 = last ? nA : cA + (size_t)(t + 2) * kstep; const char* b2 = last ? nB : cB + (size_t)(t + 2) * kstep;
;             const char* a3 = a2 + kstep; const char* b3 = b2 + kstep;
;             if (last && has_next) S.a_ready(nxt);
;             if constexpr (SP2) {
;             PG8_LDB(B0, 0, 0); PG8_LDB(B1, 0, 1); PG8_SCHED; PG8_LDA(At, 0, 0); PG8_STAGE(PG8_SA(1, 1), a1 + hstepA, voffA);
;             PG8_WAIT_V(8); PG8_WAIT_L(0); PG8_BAR; PG8_MMA(0, 0, At, B0); PG8_MMA(0, 1, At, B1); PG8_BAR; PG8_SCHED;
;             if constexpr (!HALFU) PG8_LDA(At, 0, 1); PG8_STAGE(PG8_SB(0, 0), b2, voffB); PG8_STAGE(PG8_SB(0, 1), b2 + hstep, voffB); PG8_STAGE(PG8_SA(0, 0), a2, voffA);
;             PG8_WAIT_V(8); PG8_WAIT_L(0); PG8_BAR; if constexpr (!HALFU) { PG8_MMA(1, 0, At, B0); PG8_MMA(1, 1, At, B1); } PG8_BAR; PG8_SCHED;
.LBB0_1200:
	s_add_u32 s98, s10, 0x80
	s_addc_u32 s99, s11, 0
	s_mov_b32 m0, s68
	s_nop 0
	global_load_lds_dwordx4 v136, s[98:99]
	s_mov_b32 m0, s69
	s_nop 0
	global_load_lds_dwordx4 v140, s[98:99]
	ds_read_b128 v[128:131], v149
	ds_read_b128 v[132:135], v149 offset:1024
	ds_read_b128 v[154:157], v149 offset:2048
	ds_read_b128 v[158:161], v149 offset:3072
	ds_read_b128 v[162:165], v150
	ds_read_b128 v[166:169], v150 offset:1024
	ds_read_b128 v[170:173], v150 offset:2048
	ds_read_b128 v[174:177], v150 offset:3072
	s_add_u32 s26, s10, 0x100
	s_addc_u32 s27, s11, 0
	s_cmp_eq_u32 s76, 28
	s_cselect_b32 s50, s9, s26
	s_cselect_b32 s51, s7, s27
	s_cselect_b32 s48, s43, s74
	s_cselect_b32 s49, s41, s75
	s_add_u32 s30, s50, 0x80
	s_addc_u32 s31, s51, 0
	s_add_u32 s10, s10, 0x80080
	s_addc_u32 s11, s11, 0
	s_add_i32 m0, s57, 0xc000
	ds_read_b128 v[178:181], v151
	ds_read_b128 v[182:185], v151 offset:1024
	ds_read_b128 v[186:189], v151 offset:2048
	ds_read_b128 v[190:193], v151 offset:3072
	ds_read_b128 v[194:197], v151 offset:4096
	ds_read_b128 v[198:201], v151 offset:5120
	ds_read_b128 v[202:205], v151 offset:6144
	ds_read_b128 v[206:209], v151 offset:7168
	global_load_lds_dwordx4 v136, s[10:11]
	s_add_i32 m0, s57, 0xe000
	s_nop 0
	global_load_lds_dwordx4 v140, s[10:11]
	s_waitcnt vmcnt(8) lgkmcnt(0)
	s_barrier
	v_mfma_scale_f32_16x16x128_f8f6f4 v[124:127], v[128:135], v[178:185], v[124:127], v152, v152 op_sel_hi:[0,0,0]
	v_mfma_scale_f32_16x16x128_f8f6f4 v[120:123], v[154:161], v[178:185], v[120:123], v152, v152 op_sel_hi:[0,0,0]
	v_mfma_scale_f32_16x16x128_f8f6f4 v[108:111], v[128:135], v[186:193], v[108:111], v152, v152 op_sel_hi:[0,0,0]
	v_mfma_scale_f32_16x16x128_f8f6f4 v[104:107], v[154:161], v[186:193], v[104:107], v152, v152 op_sel_hi:[0,0,0]
	v_mfma_scale_f32_16x16x128_f8f6f4 v[210:213], v[128:135], v[194:201], v[92:95], v152, v152 op_sel_hi:[0,0,0]
	v_mfma_scale_f32_16x16x128_f8f6f4 v[214:217], v[154:161], v[194:201], v[88:91], v152, v152 op_sel_hi:[0,0,0]
	v_mfma_scale_f32_16x16x128_f8f6f4 v[218:221], v[128:135], v[202:209], v[76:79], v152, v152 op_sel_hi:[0,0,0]
	v_mfma_scale_f32_16x16x128_f8f6f4 v[222:225], v[154:161], v[202:209], v[72:75], v152, v152 op_sel_hi:[0,0,0]
	v_mfma_scale_f32_16x16x128_f8f6f4 v[116:119], v[162:169], v[178:185], v[116:119], v152, v152 op_sel_hi:[0,0,0]
	v_mfma_scale_f32_16x16x128_f8f6f4 v[112:115], v[170:177], v[178:185], v[112:115], v152, v152 op_sel_hi:[0,0,0]
	v_mfma_scale_f32_16x16x128_f8f6f4 v[100:103], v[162:169], v[186:193], v[100:103], v152, v152 op_sel_hi:[0,0,0]
	v_mfma_scale_f32_16x16x128_f8f6f4 v[96:99], v[170:177], v[186:193], v[96:99], v152, v152 op_sel_hi:[0,0,0]
	v_mfma_scale_f32_16x16x128_f8f6f4 v[178:181], v[162:169], v[194:201], v[84:87], v152, v152 op_sel_hi:[0,0,0]
	v_mfma_scale_f32_16x16x128_f8f6f4 v[182:185], v[170:177], v[194:201], v[80:83], v152, v152 op_sel_hi:[0,0,0]
	v_mfma_scale_f32_16x16x128_f8f6f4 v[186:189], v[162:169], v[202:209], v[68:71], v152, v152 op_sel_hi:[0,0,0]
	v_mfma_scale_f32_16x16x128_f8f6f4 v[190:193], v[170:177], v[202:209], v[64:67], v152, v152 op_sel_hi:[0,0,0]
	s_barrier
	s_add_i32 s10, s71, s56
	s_mov_b32 m0, s10
	s_nop 1
	ds_read_b128 v[64:67], v151 offset:16384
	ds_read_b128 v[68:71], v151 offset:17408
	ds_read_b128 v[72:75], v151 offset:18432
	ds_read_b128 v[76:79], v151 offset:19456
	ds_read_b128 v[80:83], v151 offset:20480
	ds_read_b128 v[84:87], v151 offset:21504
	ds_read_b128 v[88:91], v151 offset:22528
	ds_read_b128 v[92:95], v151 offset:23552
	global_load_lds_dwordx4 v138, s[48:49]
	s_add_i32 m0, s10, 0x2000
	s_add_u32 s10, s48, 0x80000
	s_addc_u32 s11, s49, 0
	s_add_i32 s77, s72, s56
	global_load_lds_dwordx4 v142, s[48:49]
	s_mov_b32 m0, s77
	s_nop 0
	global_load_lds_dwordx4 v138, s[10:11]
	s_add_i32 m0, s77, 0x2000
	s_nop 0
	global_load_lds_dwordx4 v142, s[10:11]
	s_waitcnt vmcnt(4) lgkmcnt(0)
	s_barrier
	v_mfma_scale_f32_16x16x128_f8f6f4 v[60:63], v[128:135], v[64:71], v[60:63], v152, v152 op_sel_hi:[0,0,0]
	v_mfma_scale_f32_16x16x128_f8f6f4 v[56:59], v[154:161], v[64:71], v[56:59], v152, v152 op_sel_hi:[0,0,0]
	v_mfma_scale_f32_16x16x128_f8f6f4 v[194:197], v[128:135], v[72:79], v[44:47], v152, v152 op_sel_hi:[0,0,0]
	v_mfma_scale_f32_16x16x128_f8f6f4 v[198:201], v[154:161], v[72:79], v[40:43], v152, v152 op_sel_hi:[0,0,0]
	v_mfma_scale_f32_16x16x128_f8f6f4 v[202:205], v[128:135], v[80:87], v[28:31], v152, v152 op_sel_hi:[0,0,0]
	v_mfma_scale_f32_16x16x128_f8f6f4 v[206:209], v[154:161], v[80:87], v[24:27], v152, v152 op_sel_hi:[0,0,0]
	v_mfma_scale_f32_16x16x128_f8f6f4 v[226:229], v[128:135], v[88:95], v[12:15], v152, v152 op_sel_hi:[0,0,0]
	v_mfma_scale_f32_16x16x128_f8f6f4 v[230:233], v[154:161], v[88:95], v[8:11], v152, v152 op_sel_hi:[0,0,0]
	v_mfma_scale_f32_16x16x128_f8f6f4 v[52:55], v[162:169], v[64:71], v[52:55], v152, v152 op_sel_hi:[0,0,0]
	v_mfma_scale_f32_16x16x128_f8f6f4 v[48:51], v[170:177], v[64:71], v[48:51], v152, v152 op_sel_hi:[0,0,0]
	v_mfma_scale_f32_16x16x128_f8f6f4 v[234:237], v[162:169], v[72:79], v[36:39], v152, v152 op_sel_hi:[0,0,0]
	v_mfma_scale_f32_16x16x128_f8f6f4 v[238:241], v[170:177], v[72:79], v[32:35], v152, v152 op_sel_hi:[0,0,0]
	v_mfma_scale_f32_16x16x128_f8f6f4 v[242:245], v[162:169], v[80:87], v[20:23], v152, v152 op_sel_hi:[0,0,0]
	v_mfma_scale_f32_16x16x128_f8f6f4 v[246:249], v[170:177], v[80:87], v[16:19], v152, v152 op_sel_hi:[0,0,0]
	v_mfma_scale_f32_16x16x128_f8f6f4 v[250:253], v[162:169], v[88:95], v[4:7], v152, v152 op_sel_hi:[0,0,0]
	v_mfma_scale_f32_16x16x128_f8f6f4 v[144:147], v[170:177], v[88:95], v[0:3], v152, v152 op_sel_hi:[0,0,0]
	s_barrier
; #define PG8_WAIT_V(n) asm volatile("s_waitcnt vmcnt(" #n ")" ::: "memory")
; #define PG8_WAIT_L(n) asm volatile("s_waitcnt lgkmcnt(" #n ")" ::: "memory")
; #define PG8_BAR __builtin_amdgcn_s_barrier()
; #define PG8_SCHED __builtin_amdgcn_sched_barrier(0)
;     ...
;         for (int t = 0; t < nt; t += 2) {
;     ...
;             PG8_LDB(B0, 1, 0); PG8_LDB(B1, 1, 1); PG8_SCHED; PG8_LDA(At, 1, 0); PG8_STAGE(PG8_SA(0, 1), a2 + hstepA, voffA);
;             PG8_WAIT_V(8); PG8_WAIT_L(0); PG8_BAR; PG8_MMA(0, 0, At, B0); PG8_MMA(0, 1, At, B1); PG8_BAR; PG8_SCHED;
;             if constexpr (!HALFU) PG8_LDA(At, 1, 1); PG8_STAGE(PG8_SB(1, 0), b3, voffB); PG8_STAGE(PG8_SB(1, 1), b3 + hstep, voffB); PG8_STAGE(PG8_SA(1, 0), a3, voffA);
;             PG8_WAIT_V(8); PG8_WAIT_L(0); PG8_BAR; if constexpr (!HALFU) { PG8_MMA(1, 0, At, B0); PG8_MMA(1, 1, At, B1); } PG8_BAR; PG8_SCHED;
	s_mov_b32 m0, s57
	s_nop 0
	global_load_lds_dwordx4 v136, s[50:51]
	s_mov_b32 m0, s62
	s_nop 0
	global_load_lds_dwordx4 v140, s[50:51]
	s_add_i32 s77, 0, 0x18000
	v_add_u32_e32 v8, s77, v148
	s_add_i32 s78, 0, 0x1c000
	s_nop 1
	ds_read_b128 v[0:3], v8
	ds_read_b128 v[4:7], v8 offset:1024
	ds_read_b128 v[16:19], v8 offset:2048
	ds_read_b128 v[20:23], v8 offset:3072
	v_add_u32_e32 v8, s78, v148
	ds_read_b128 v[128:131], v8
	ds_read_b128 v[132:135], v8 offset:1024
	ds_read_b128 v[154:157], v8 offset:2048
	ds_read_b128 v[158:161], v8 offset:3072
	s_add_u32 s10, s50, 0x80000
	s_addc_u32 s11, s51, 0
	s_mov_b32 m0, s63
	ds_read_b128 v[8:11], v151 offset:32768
	ds_read_b128 v[12:15], v151 offset:33792
	ds_read_b128 v[24:27], v151 offset:34816
	ds_read_b128 v[28:31], v151 offset:35840
	ds_read_b128 v[32:35], v151 offset:36864
	ds_read_b128 v[36:39], v151 offset:37888
	ds_read_b128 v[40:43], v151 offset:38912
	ds_read_b128 v[44:47], v151 offset:39936
	global_load_lds_dwordx4 v136, s[10:11]
	s_mov_b32 m0, s64
	s_nop 0
	global_load_lds_dwordx4 v140, s[10:11]
	s_waitcnt vmcnt(8) lgkmcnt(0)
	s_barrier
	v_mfma_scale_f32_16x16x128_f8f6f4 v[124:127], v[0:7], v[8:15], v[124:127], v152, v152 op_sel_hi:[0,0,0]
	v_mfma_scale_f32_16x16x128_f8f6f4 v[120:123], v[16:23], v[8:15], v[120:123], v152, v152 op_sel_hi:[0,0,0]
	v_mfma_scale_f32_16x16x128_f8f6f4 v[108:111], v[0:7], v[24:31], v[108:111], v152, v152 op_sel_hi:[0,0,0]
	v_mfma_scale_f32_16x16x128_f8f6f4 v[104:107], v[16:23], v[24:31], v[104:107], v152, v152 op_sel_hi:[0,0,0]
	v_mfma_scale_f32_16x16x128_f8f6f4 v[92:95], v[0:7], v[32:39], v[210:213], v152, v152 op_sel_hi:[0,0,0]
	v_mfma_scale_f32_16x16x128_f8f6f4 v[88:91], v[16:23], v[32:39], v[214:217], v152, v152 op_sel_hi:[0,0,0]
	v_mfma_scale_f32_16x16x128_f8f6f4 v[76:79], v[0:7], v[40:47], v[218:221], v152, v152 op_sel_hi:[0,0,0]
	v_mfma_scale_f32_16x16x128_f8f6f4 v[72:75], v[16:23], v[40:47], v[222:225], v152, v152 op_sel_hi:[0,0,0]
	v_mfma_scale_f32_16x16x128_f8f6f4 v[116:119], v[128:135], v[8:15], v[116:119], v152, v152 op_sel_hi:[0,0,0]
	v_mfma_scale_f32_16x16x128_f8f6f4 v[112:115], v[154:161], v[8:15], v[112:115], v152, v152 op_sel_hi:[0,0,0]
	v_mfma_scale_f32_16x16x128_f8f6f4 v[100:103], v[128:135], v[24:31], v[100:103], v152, v152 op_sel_hi:[0,0,0]
	v_mfma_scale_f32_16x16x128_f8f6f4 v[96:99], v[154:161], v[24:31], v[96:99], v152, v152 op_sel_hi:[0,0,0]
	v_mfma_scale_f32_16x16x128_f8f6f4 v[84:87], v[128:135], v[32:39], v[178:181], v152, v152 op_sel_hi:[0,0,0]
	v_mfma_scale_f32_16x16x128_f8f6f4 v[80:83], v[154:161], v[32:39], v[182:185], v152, v152 op_sel_hi:[0,0,0]
	v_mfma_scale_f32_16x16x128_f8f6f4 v[68:71], v[128:135], v[40:47], v[186:189], v152, v152 op_sel_hi:[0,0,0]
	v_mfma_scale_f32_16x16x128_f8f6f4 v[64:67], v[154:161], v[40:47], v[190:193], v152, v152 op_sel_hi:[0,0,0]
	s_barrier
	s_add_u32 s10, s48, 0x80
	s_addc_u32 s11, s49, 0
	s_add_i32 s50, s77, s56
	s_mov_b32 m0, s50
	ds_read_b128 v[32:35], v151 offset:49152
	ds_read_b128 v[36:39], v151 offset:50176
	ds_read_b128 v[162:165], v151 offset:51200
	ds_read_b128 v[166:169], v151 offset:52224
	ds_read_b128 v[170:173], v151 offset:53248
	ds_read_b128 v[174:177], v151 offset:54272
	ds_read_b128 v[178:181], v151 offset:55296
	ds_read_b128 v[182:185], v151 offset:56320
	global_load_lds_dwordx4 v138, s[10:11]
	s_add_i32 m0, s50, 0x2000
	v_lshl_add_u64 v[8:9], s[10:11], 0, v[142:143]
	s_add_u32 s10, s48, 0x80080
	s_addc_u32 s11, s49, 0
	s_add_i32 s48, s78, s56
	global_load_lds_dwordx4 v[8:9], off
	s_mov_b32 m0, s48
	s_nop 0
	global_load_lds_dwordx4 v138, s[10:11]
	s_add_i32 m0, s48, 0x2000
	s_nop 0
	global_load_lds_dwordx4 v142, s[10:11]
	s_waitcnt vmcnt(4) lgkmcnt(0)
	s_barrier
	v_mfma_scale_f32_16x16x128_f8f6f4 v[60:63], v[0:7], v[32:39], v[60:63], v152, v152 op_sel_hi:[0,0,0]
	v_mfma_scale_f32_16x16x128_f8f6f4 v[56:59], v[16:23], v[32:39], v[56:59], v152, v152 op_sel_hi:[0,0,0]
	v_mfma_scale_f32_16x16x128_f8f6f4 v[44:47], v[0:7], v[162:169], v[194:197], v152, v152 op_sel_hi:[0,0,0]
	v_mfma_scale_f32_16x16x128_f8f6f4 v[40:43], v[16:23], v[162:169], v[198:201], v152, v152 op_sel_hi:[0,0,0]
	v_mfma_scale_f32_16x16x128_f8f6f4 v[28:31], v[0:7], v[170:177], v[202:205], v152, v152 op_sel_hi:[0,0,0]
	v_mfma_scale_f32_16x16x128_f8f6f4 v[24:27], v[16:23], v[170:177], v[206:209], v152, v152 op_sel_hi:[0,0,0]
	v_mfma_scale_f32_16x16x128_f8f6f4 v[12:15], v[0:7], v[178:185], v[226:229], v152, v152 op_sel_hi:[0,0,0]
	v_mfma_scale_f32_16x16x128_f8f6f4 v[8:11], v[16:23], v[178:185], v[230:233], v152, v152 op_sel_hi:[0,0,0]
	v_mfma_scale_f32_16x16x128_f8f6f4 v[52:55], v[128:135], v[32:39], v[52:55], v152, v152 op_sel_hi:[0,0,0]
	v_mfma_scale_f32_16x16x128_f8f6f4 v[48:51], v[154:161], v[32:39], v[48:51], v152, v152 op_sel_hi:[0,0,0]
	v_mfma_scale_f32_16x16x128_f8f6f4 v[36:39], v[128:135], v[162:169], v[234:237], v152, v152 op_sel_hi:[0,0,0]
	v_mfma_scale_f32_16x16x128_f8f6f4 v[32:35], v[154:161], v[162:169], v[238:241], v152, v152 op_sel_hi:[0,0,0]
	v_mfma_scale_f32_16x16x128_f8f6f4 v[20:23], v[128:135], v[170:177], v[242:245], v152, v152 op_sel_hi:[0,0,0]
	v_mfma_scale_f32_16x16x128_f8f6f4 v[16:19], v[154:161], v[170:177], v[246:249], v152, v152 op_sel_hi:[0,0,0]
	v_mfma_scale_f32_16x16x128_f8f6f4 v[4:7], v[128:135], v[178:185], v[250:253], v152, v152 op_sel_hi:[0,0,0]
	v_mfma_scale_f32_16x16x128_f8f6f4 v[0:3], v[154:161], v[178:185], v[144:147], v152, v152 op_sel_hi:[0,0,0]
	s_barrier
	s_add_i32 s76, s76, 2
	s_add_u32 s74, s74, 0x100
	s_addc_u32 s75, s75, 0
	s_cmp_gt_u32 s76, 29
	s_mov_b64 s[10:11], s[26:27]
	s_cbranch_scc0 .LBB0_1200
	s_and_b64 vcc, exec, s[36:37]
	s_cbranch_vccz .LBB0_1203
	s_barrier

; #define PG8_WAIT_V(n) asm volatile("s_waitcnt vmcnt(" #n ")" ::: "memory")
; #define PG8_WAIT_L(n) asm volatile("s_waitcnt lgkmcnt(" #n ")" ::: "memory")
; #define PG8_BAR __builtin_amdgcn_s_barrier()
; #define PG8_SCHED __builtin_amdgcn_sched_barrier(0)
;     ...
;             const char* a1 = cA + (size_t)(t + 1) * kstep;
;             const char* a2 = last ? nA : cA + (size_t)(t + 2) * kstep; const char* b2 = last ? nB : cB + (size_t)(t + 2) * kstep;
;             const char* a3 = a2 + kstep; const char* b3 = b2 + kstep;
;             if (last && has_next) S.a_ready(nxt);
;             if constexpr (SP2) {
;             PG8_LDB(B0, 0, 0); PG8_LDB(B1, 0, 1); PG8_SCHED; PG8_LDA(At, 0, 0); PG8_STAGE(PG8_SA(1, 1), a1 + hstepA, voffA);
;             PG8_WAIT_V(8); PG8_WAIT_L(0); PG8_BAR; PG8_MMA(0, 0, At, B0); PG8_MMA(0, 1, At, B1); PG8_BAR; PG8_SCHED;
;             if constexpr (!HALFU) PG8_LDA(At, 0, 1); PG8_STAGE(PG8_SB(0, 0), b2, voffB); PG8_STAGE(PG8_SB(0, 1), b2 + hstep, voffB); PG8_STAGE(PG8_SA(0, 0), a2, voffA);
;             PG8_WAIT_V(8); PG8_WAIT_L(0); PG8_BAR; if constexpr (!HALFU) { PG8_MMA(1, 0, At, B0); PG8_MMA(1, 1, At, B1); } PG8_BAR; PG8_SCHED;
.LBB0_1370:
	s_add_u32 s98, s10, 0x80
	s_addc_u32 s99, s11, 0
	s_mov_b32 m0, s67
	s_nop 0
	global_load_lds_dwordx4 v136, s[98:99]
	s_mov_b32 m0, s68
	s_nop 0
	global_load_lds_dwordx4 v140, s[98:99]
	ds_read_b128 v[128:131], v163
	ds_read_b128 v[132:135], v163 offset:1024
	ds_read_b128 v[150:153], v163 offset:2048
	ds_read_b128 v[154:157], v163 offset:3072
	ds_read_b128 v[158:161], v164
	ds_read_b128 v[166:169], v164 offset:1024
	ds_read_b128 v[170:173], v164 offset:2048
	ds_read_b128 v[174:177], v164 offset:3072
	s_add_u32 s12, s10, 0x100
	s_addc_u32 s13, s11, 0
	s_cmp_eq_u32 s53, 60
	s_cselect_b32 s50, s7, s12
	s_cselect_b32 s51, s0, s13
	s_cselect_b32 s48, s39, s41
	s_cselect_b32 s49, s9, s52
	s_add_u32 s46, s50, 0x80
	s_addc_u32 s47, s51, 0
	s_add_u32 s10, s10, 0x100080
	s_addc_u32 s11, s11, 0
	s_add_i32 m0, s37, 0xc000
	ds_read_b128 v[178:181], v165
	ds_read_b128 v[182:185], v165 offset:1024
	ds_read_b128 v[186:189], v165 offset:2048
	ds_read_b128 v[190:193], v165 offset:3072
	ds_read_b128 v[194:197], v165 offset:4096
	ds_read_b128 v[198:201], v165 offset:5120
	ds_read_b128 v[202:205], v165 offset:6144
	ds_read_b128 v[206:209], v165 offset:7168
	global_load_lds_dwordx4 v136, s[10:11]
	s_add_i32 m0, s37, 0xe000
	s_nop 0
	global_load_lds_dwordx4 v140, s[10:11]
	s_waitcnt vmcnt(8) lgkmcnt(0)
	s_barrier
	v_mfma_f32_16x16x32_bf16 v[124:127], v[128:131], v[178:181], v[124:127]
	v_mfma_f32_16x16x32_bf16 v[120:123], v[150:153], v[178:181], v[120:123]
	v_mfma_f32_16x16x32_bf16 v[108:111], v[128:131], v[186:189], v[108:111]
	v_mfma_f32_16x16x32_bf16 v[104:107], v[150:153], v[186:189], v[104:107]
	v_mfma_f32_16x16x32_bf16 v[92:95], v[128:131], v[194:197], v[92:95]
	v_mfma_f32_16x16x32_bf16 v[88:91], v[150:153], v[194:197], v[88:91]
	v_mfma_f32_16x16x32_bf16 v[76:79], v[128:131], v[202:205], v[76:79]
	v_mfma_f32_16x16x32_bf16 v[72:75], v[150:153], v[202:205], v[72:75]
	v_mfma_f32_16x16x32_bf16 v[124:127], v[132:135], v[182:185], v[124:127]
	v_mfma_f32_16x16x32_bf16 v[120:123], v[154:157], v[182:185], v[120:123]
	v_mfma_f32_16x16x32_bf16 v[108:111], v[132:135], v[190:193], v[108:111]
	v_mfma_f32_16x16x32_bf16 v[104:107], v[154:157], v[190:193], v[104:107]
	v_mfma_f32_16x16x32_bf16 v[92:95], v[132:135], v[198:201], v[92:95]
	v_mfma_f32_16x16x32_bf16 v[88:91], v[154:157], v[198:201], v[88:91]
	v_mfma_f32_16x16x32_bf16 v[76:79], v[132:135], v[206:209], v[76:79]
	v_mfma_f32_16x16x32_bf16 v[72:75], v[154:157], v[206:209], v[72:75]
	v_mfma_f32_16x16x32_bf16 v[116:119], v[158:161], v[178:181], v[116:119]
	v_mfma_f32_16x16x32_bf16 v[112:115], v[170:173], v[178:181], v[112:115]
	v_mfma_f32_16x16x32_bf16 v[100:103], v[158:161], v[186:189], v[100:103]
	v_mfma_f32_16x16x32_bf16 v[96:99], v[170:173], v[186:189], v[96:99]
	v_mfma_f32_16x16x32_bf16 v[84:87], v[158:161], v[194:197], v[84:87]
	v_mfma_f32_16x16x32_bf16 v[80:83], v[170:173], v[194:197], v[80:83]
	v_mfma_f32_16x16x32_bf16 v[68:71], v[158:161], v[202:205], v[68:71]
	v_mfma_f32_16x16x32_bf16 v[64:67], v[170:173], v[202:205], v[64:67]
	v_mfma_f32_16x16x32_bf16 v[116:119], v[166:169], v[182:185], v[116:119]
	v_mfma_f32_16x16x32_bf16 v[112:115], v[174:177], v[182:185], v[112:115]
	v_mfma_f32_16x16x32_bf16 v[100:103], v[166:169], v[190:193], v[100:103]
	v_mfma_f32_16x16x32_bf16 v[96:99], v[174:177], v[190:193], v[96:99]
	v_mfma_f32_16x16x32_bf16 v[84:87], v[166:169], v[198:201], v[84:87]
	v_mfma_f32_16x16x32_bf16 v[80:83], v[174:177], v[198:201], v[80:83]
	v_mfma_f32_16x16x32_bf16 v[68:71], v[166:169], v[206:209], v[68:71]
	v_mfma_f32_16x16x32_bf16 v[64:67], v[174:177], v[206:209], v[64:67]
	s_barrier
	s_add_i32 s10, s71, s21
	s_mov_b32 m0, s10
	ds_read_b128 v[178:181], v165 offset:16384
	ds_read_b128 v[182:185], v165 offset:17408
	ds_read_b128 v[186:189], v165 offset:18432
	ds_read_b128 v[190:193], v165 offset:19456
	ds_read_b128 v[194:197], v165 offset:20480
	ds_read_b128 v[198:201], v165 offset:21504
	ds_read_b128 v[202:205], v165 offset:22528
	ds_read_b128 v[206:209], v165 offset:23552
	global_load_lds_dwordx4 v138, s[48:49]
	s_add_i32 m0, s10, 0x2000
	s_add_u32 s10, s48, 0x100000
	s_addc_u32 s11, s49, 0
	s_add_i32 s54, s72, s21
	global_load_lds_dwordx4 v142, s[48:49]
	s_mov_b32 m0, s54
	s_nop 0
	global_load_lds_dwordx4 v138, s[10:11]
	s_add_i32 m0, s54, 0x2000
	s_nop 0
	global_load_lds_dwordx4 v142, s[10:11]
	s_waitcnt vmcnt(4) lgkmcnt(0)
	s_barrier
	v_mfma_f32_16x16x32_bf16 v[60:63], v[128:131], v[178:181], v[60:63]
	v_mfma_f32_16x16x32_bf16 v[56:59], v[150:153], v[178:181], v[56:59]
	v_mfma_f32_16x16x32_bf16 v[44:47], v[128:131], v[186:189], v[44:47]
	v_mfma_f32_16x16x32_bf16 v[40:43], v[150:153], v[186:189], v[40:43]
	v_mfma_f32_16x16x32_bf16 v[28:31], v[128:131], v[194:197], v[28:31]
	v_mfma_f32_16x16x32_bf16 v[24:27], v[150:153], v[194:197], v[24:27]
	v_mfma_f32_16x16x32_bf16 v[12:15], v[128:131], v[202:205], v[12:15]
	v_mfma_f32_16x16x32_bf16 v[8:11], v[150:153], v[202:205], v[8:11]
	v_mfma_f32_16x16x32_bf16 v[60:63], v[132:135], v[182:185], v[60:63]
	v_mfma_f32_16x16x32_bf16 v[56:59], v[154:157], v[182:185], v[56:59]
	v_mfma_f32_16x16x32_bf16 v[44:47], v[132:135], v[190:193], v[44:47]
	v_mfma_f32_16x16x32_bf16 v[40:43], v[154:157], v[190:193], v[40:43]
	v_mfma_f32_16x16x32_bf16 v[28:31], v[132:135], v[198:201], v[28:31]
	v_mfma_f32_16x16x32_bf16 v[24:27], v[154:157], v[198:201], v[24:27]
	v_mfma_f32_16x16x32_bf16 v[12:15], v[132:135], v[206:209], v[12:15]
	v_mfma_f32_16x16x32_bf16 v[8:11], v[154:157], v[206:209], v[8:11]
	v_mfma_f32_16x16x32_bf16 v[52:55], v[158:161], v[178:181], v[52:55]
	v_mfma_f32_16x16x32_bf16 v[48:51], v[170:173], v[178:181], v[48:51]
	v_mfma_f32_16x16x32_bf16 v[36:39], v[158:161], v[186:189], v[36:39]
	v_mfma_f32_16x16x32_bf16 v[32:35], v[170:173], v[186:189], v[32:35]
	v_mfma_f32_16x16x32_bf16 v[20:23], v[158:161], v[194:197], v[20:23]
	v_mfma_f32_16x16x32_bf16 v[16:19], v[170:173], v[194:197], v[16:19]
	v_mfma_f32_16x16x32_bf16 v[4:7], v[158:161], v[202:205], v[4:7]
	v_mfma_f32_16x16x32_bf16 v[0:3], v[170:173], v[202:205], v[0:3]
	v_mfma_f32_16x16x32_bf16 v[52:55], v[166:169], v[182:185], v[52:55]
	v_mfma_f32_16x16x32_bf16 v[48:51], v[174:177], v[182:185], v[48:51]
	v_mfma_f32_16x16x32_bf16 v[36:39], v[166:169], v[190:193], v[36:39]
	v_mfma_f32_16x16x32_bf16 v[32:35], v[174:177], v[190:193], v[32:35]
	v_mfma_f32_16x16x32_bf16 v[20:23], v[166:169], v[198:201], v[20:23]
	v_mfma_f32_16x16x32_bf16 v[16:19], v[174:177], v[198:201], v[16:19]
	v_mfma_f32_16x16x32_bf16 v[4:7], v[166:169], v[206:209], v[4:7]
	v_mfma_f32_16x16x32_bf16 v[0:3], v[174:177], v[206:209], v[0:3]
	s_barrier
; #define PG8_WAIT_V(n) asm volatile("s_waitcnt vmcnt(" #n ")" ::: "memory")
; #define PG8_WAIT_L(n) asm volatile("s_waitcnt lgkmcnt(" #n ")" ::: "memory")
; #define PG8_BAR __builtin_amdgcn_s_barrier()
; #define PG8_SCHED __builtin_amdgcn_sched_barrier(0)
;     ...
;         for (int t = 0; t < nt; t += 2) {
;     ...
;             PG8_LDB(B0, 1, 0); PG8_LDB(B1, 1, 1); PG8_SCHED; PG8_LDA(At, 1, 0); PG8_STAGE(PG8_SA(0, 1), a2 + hstepA, voffA);
;             PG8_WAIT_V(8); PG8_WAIT_L(0); PG8_BAR; PG8_MMA(0, 0, At, B0); PG8_MMA(0, 1, At, B1); PG8_BAR; PG8_SCHED;
;             if constexpr (!HALFU) PG8_LDA(At, 1, 1); PG8_STAGE(PG8_SB(1, 0), b3, voffB); PG8_STAGE(PG8_SB(1, 1), b3 + hstep, voffB); PG8_STAGE(PG8_SA(1, 0), a3, voffA);
;             PG8_WAIT_V(8); PG8_WAIT_L(0); PG8_BAR; if constexpr (!HALFU) { PG8_MMA(1, 0, At, B0); PG8_MMA(1, 1, At, B1); } PG8_BAR; PG8_SCHED;
	s_mov_b32 m0, s37
	s_nop 0
	global_load_lds_dwordx4 v136, s[50:51]
	s_mov_b32 m0, s62
	s_nop 0
	global_load_lds_dwordx4 v140, s[50:51]
	s_add_i32 s54, 0, 0x18000
	v_add_u32_e32 v144, s54, v162
	s_add_i32 s55, 0, 0x1c000
	ds_read_b128 v[128:131], v144
	ds_read_b128 v[132:135], v144 offset:1024
	ds_read_b128 v[150:153], v144 offset:2048
	ds_read_b128 v[154:157], v144 offset:3072
	v_add_u32_e32 v144, s55, v162
	ds_read_b128 v[158:161], v144
	ds_read_b128 v[166:169], v144 offset:1024
	ds_read_b128 v[170:173], v144 offset:2048
	ds_read_b128 v[174:177], v144 offset:3072
	s_add_u32 s10, s50, 0x100000
	s_addc_u32 s11, s51, 0
	s_mov_b32 m0, s63
	ds_read_b128 v[178:181], v165 offset:32768
	ds_read_b128 v[182:185], v165 offset:33792
	ds_read_b128 v[186:189], v165 offset:34816
	ds_read_b128 v[190:193], v165 offset:35840
	ds_read_b128 v[194:197], v165 offset:36864
	ds_read_b128 v[198:201], v165 offset:37888
	ds_read_b128 v[202:205], v165 offset:38912
	ds_read_b128 v[206:209], v165 offset:39936
	global_load_lds_dwordx4 v136, s[10:11]
	s_mov_b32 m0, s64
	s_nop 0
	global_load_lds_dwordx4 v140, s[10:11]
	s_waitcnt vmcnt(8) lgkmcnt(0)
	s_barrier
	v_mfma_f32_16x16x32_bf16 v[124:127], v[128:131], v[178:181], v[124:127]
	v_mfma_f32_16x16x32_bf16 v[120:123], v[150:153], v[178:181], v[120:123]
	v_mfma_f32_16x16x32_bf16 v[108:111], v[128:131], v[186:189], v[108:111]
	v_mfma_f32_16x16x32_bf16 v[104:107], v[150:153], v[186:189], v[104:107]
	v_mfma_f32_16x16x32_bf16 v[92:95], v[128:131], v[194:197], v[92:95]
	v_mfma_f32_16x16x32_bf16 v[88:91], v[150:153], v[194:197], v[88:91]
	v_mfma_f32_16x16x32_bf16 v[76:79], v[128:131], v[202:205], v[76:79]
	v_mfma_f32_16x16x32_bf16 v[72:75], v[150:153], v[202:205], v[72:75]
	v_mfma_f32_16x16x32_bf16 v[124:127], v[132:135], v[182:185], v[124:127]
	v_mfma_f32_16x16x32_bf16 v[120:123], v[154:157], v[182:185], v[120:123]
	v_mfma_f32_16x16x32_bf16 v[108:111], v[132:135], v[190:193], v[108:111]
	v_mfma_f32_16x16x32_bf16 v[104:107], v[154:157], v[190:193], v[104:107]
	v_mfma_f32_16x16x32_bf16 v[92:95], v[132:135], v[198:201], v[92:95]
	v_mfma_f32_16x16x32_bf16 v[88:91], v[154:157], v[198:201], v[88:91]
	v_mfma_f32_16x16x32_bf16 v[76:79], v[132:135], v[206:209], v[76:79]
	v_mfma_f32_16x16x32_bf16 v[72:75], v[154:157], v[206:209], v[72:75]
	v_mfma_f32_16x16x32_bf16 v[116:119], v[158:161], v[178:181], v[116:119]
	v_mfma_f32_16x16x32_bf16 v[112:115], v[170:173], v[178:181], v[112:115]
	v_mfma_f32_16x16x32_bf16 v[100:103], v[158:161], v[186:189], v[100:103]
	v_mfma_f32_16x16x32_bf16 v[96:99], v[170:173], v[186:189], v[96:99]
	v_mfma_f32_16x16x32_bf16 v[84:87], v[158:161], v[194:197], v[84:87]
	v_mfma_f32_16x16x32_bf16 v[80:83], v[170:173], v[194:197], v[80:83]
	v_mfma_f32_16x16x32_bf16 v[68:71], v[158:161], v[202:205], v[68:71]
	v_mfma_f32_16x16x32_bf16 v[64:67], v[170:173], v[202:205], v[64:67]
	v_mfma_f32_16x16x32_bf16 v[116:119], v[166:169], v[182:185], v[116:119]
	v_mfma_f32_16x16x32_bf16 v[112:115], v[174:177], v[182:185], v[112:115]
	v_mfma_f32_16x16x32_bf16 v[100:103], v[166:169], v[190:193], v[100:103]
	v_mfma_f32_16x16x32_bf16 v[96:99], v[174:177], v[190:193], v[96:99]
	v_mfma_f32_16x16x32_bf16 v[84:87], v[166:169], v[198:201], v[84:87]
	v_mfma_f32_16x16x32_bf16 v[80:83], v[174:177], v[198:201], v[80:83]
	v_mfma_f32_16x16x32_bf16 v[68:71], v[166:169], v[206:209], v[68:71]
	v_mfma_f32_16x16x32_bf16 v[64:67], v[174:177], v[206:209], v[64:67]
	s_barrier
	s_add_u32 s10, s48, 0x80
	s_addc_u32 s11, s49, 0
	s_add_i32 s50, s54, s21
	s_mov_b32 m0, s50
	ds_read_b128 v[178:181], v165 offset:49152
	ds_read_b128 v[182:185], v165 offset:50176
	ds_read_b128 v[186:189], v165 offset:51200
	ds_read_b128 v[190:193], v165 offset:52224
	ds_read_b128 v[194:197], v165 offset:53248
	ds_read_b128 v[198:201], v165 offset:54272
	ds_read_b128 v[202:205], v165 offset:55296
	ds_read_b128 v[206:209], v165 offset:56320
	global_load_lds_dwordx4 v138, s[10:11]
	s_add_i32 m0, s50, 0x2000
	v_lshl_add_u64 v[210:211], s[10:11], 0, v[142:143]
	s_add_u32 s10, s48, 0x100080
	s_addc_u32 s11, s49, 0
	s_add_i32 s48, s55, s21
	global_load_lds_dwordx4 v[210:211], off
	s_mov_b32 m0, s48
	s_nop 0
	global_load_lds_dwordx4 v138, s[10:11]
	s_add_i32 m0, s48, 0x2000
	s_nop 0
	global_load_lds_dwordx4 v142, s[10:11]
	s_waitcnt vmcnt(4) lgkmcnt(0)
	s_barrier
	v_mfma_f32_16x16x32_bf16 v[60:63], v[128:131], v[178:181], v[60:63]
	v_mfma_f32_16x16x32_bf16 v[56:59], v[150:153], v[178:181], v[56:59]
	v_mfma_f32_16x16x32_bf16 v[44:47], v[128:131], v[186:189], v[44:47]
	v_mfma_f32_16x16x32_bf16 v[40:43], v[150:153], v[186:189], v[40:43]
	v_mfma_f32_16x16x32_bf16 v[28:31], v[128:131], v[194:197], v[28:31]
	v_mfma_f32_16x16x32_bf16 v[24:27], v[150:153], v[194:197], v[24:27]
	v_mfma_f32_16x16x32_bf16 v[12:15], v[128:131], v[202:205], v[12:15]
	v_mfma_f32_16x16x32_bf16 v[8:11], v[150:153], v[202:205], v[8:11]
	v_mfma_f32_16x16x32_bf16 v[60:63], v[132:135], v[182:185], v[60:63]
	v_mfma_f32_16x16x32_bf16 v[56:59], v[154:157], v[182:185], v[56:59]
	v_mfma_f32_16x16x32_bf16 v[44:47], v[132:135], v[190:193], v[44:47]
	v_mfma_f32_16x16x32_bf16 v[40:43], v[154:157], v[190:193], v[40:43]
	v_mfma_f32_16x16x32_bf16 v[28:31], v[132:135], v[198:201], v[28:31]
	v_mfma_f32_16x16x32_bf16 v[24:27], v[154:157], v[198:201], v[24:27]
	v_mfma_f32_16x16x32_bf16 v[12:15], v[132:135], v[206:209], v[12:15]
	v_mfma_f32_16x16x32_bf16 v[8:11], v[154:157], v[206:209], v[8:11]
	v_mfma_f32_16x16x32_bf16 v[52:55], v[158:161], v[178:181], v[52:55]
	v_mfma_f32_16x16x32_bf16 v[48:51], v[170:173], v[178:181], v[48:51]
	v_mfma_f32_16x16x32_bf16 v[36:39], v[158:161], v[186:189], v[36:39]
	v_mfma_f32_16x16x32_bf16 v[32:35], v[170:173], v[186:189], v[32:35]
	v_mfma_f32_16x16x32_bf16 v[20:23], v[158:161], v[194:197], v[20:23]
	v_mfma_f32_16x16x32_bf16 v[16:19], v[170:173], v[194:197], v[16:19]
	v_mfma_f32_16x16x32_bf16 v[4:7], v[158:161], v[202:205], v[4:7]
	v_mfma_f32_16x16x32_bf16 v[0:3], v[170:173], v[202:205], v[0:3]
	v_mfma_f32_16x16x32_bf16 v[52:55], v[166:169], v[182:185], v[52:55]
	v_mfma_f32_16x16x32_bf16 v[48:51], v[174:177], v[182:185], v[48:51]
	v_mfma_f32_16x16x32_bf16 v[36:39], v[166:169], v[190:193], v[36:39]
	v_mfma_f32_16x16x32_bf16 v[32:35], v[174:177], v[190:193], v[32:35]
	v_mfma_f32_16x16x32_bf16 v[20:23], v[166:169], v[198:201], v[20:23]
	v_mfma_f32_16x16x32_bf16 v[16:19], v[174:177], v[198:201], v[16:19]
	v_mfma_f32_16x16x32_bf16 v[4:7], v[166:169], v[206:209], v[4:7]
	v_mfma_f32_16x16x32_bf16 v[0:3], v[174:177], v[206:209], v[0:3]
	s_barrier
	s_add_i32 s53, s53, 2
	s_add_u32 s41, s41, 0x100
	s_addc_u32 s52, s52, 0
	s_cmp_gt_u32 s53, 61
	s_mov_b64 s[10:11], s[12:13]
	s_cbranch_scc0 .LBB0_1370
	s_and_b64 vcc, exec, s[28:29]
	s_cbranch_vccz .LBB0_1373
	s_barrier

; #define PG8_WAIT_V(n) asm volatile("s_waitcnt vmcnt(" #n ")" ::: "memory")
; #define PG8_WAIT_L(n) asm volatile("s_waitcnt lgkmcnt(" #n ")" ::: "memory")
; #define PG8_BAR __builtin_amdgcn_s_barrier()
; #define PG8_SCHED __builtin_amdgcn_sched_barrier(0)
;     ...
;             const char* a1 = cA + (size_t)(t + 1) * kstep;
;             const char* a2 = last ? nA : cA + (size_t)(t + 2) * kstep; const char* b2 = last ? nB : cB + (size_t)(t + 2) * kstep;
;             const char* a3 = a2 + kstep; const char* b3 = b2 + kstep;
;             if (last && has_next) S.a_ready(nxt);
;             if constexpr (SP2) {
;             PG8_LDB(B0, 0, 0); PG8_LDB(B1, 0, 1); PG8_SCHED; PG8_LDA(At, 0, 0); PG8_STAGE(PG8_SA(1, 1), a1 + hstepA, voffA);
;             PG8_WAIT_V(8); PG8_WAIT_L(0); PG8_BAR; PG8_MMA(0, 0, At, B0); PG8_MMA(0, 1, At, B1); PG8_BAR; PG8_SCHED;
;             if constexpr (!HALFU) PG8_LDA(At, 0, 1); PG8_STAGE(PG8_SB(0, 0), b2, voffB); PG8_STAGE(PG8_SB(0, 1), b2 + hstep, voffB); PG8_STAGE(PG8_SA(0, 0), a2, voffA);
;             PG8_WAIT_V(8); PG8_WAIT_L(0); PG8_BAR; if constexpr (!HALFU) { PG8_MMA(1, 0, At, B0); PG8_MMA(1, 1, At, B1); } PG8_BAR; PG8_SCHED;
.LBB0_3426:
	s_sub_u32 s98, s28, 0x80000
	s_subb_u32 s99, s29, 0
	s_mov_b32 m0, s50
	s_nop 0
	global_load_lds_dwordx4 v128, s[98:99]
	s_mov_b32 m0, s51
	s_nop 0
	global_load_lds_dwordx4 v130, s[98:99]
	ds_read_b128 v[142:145], v137
	ds_read_b128 v[146:149], v137 offset:1024
	ds_read_b128 v[150:153], v137 offset:2048
	ds_read_b128 v[154:157], v137 offset:3072
	ds_read_b128 v[158:161], v138
	ds_read_b128 v[162:165], v138 offset:1024
	ds_read_b128 v[166:169], v138 offset:2048
	ds_read_b128 v[170:173], v138 offset:3072
	s_cmp_eq_u32 s62, 28
	s_cselect_b32 s38, s55, s57
	s_cselect_b32 s39, s23, s59
	s_cselect_b32 s36, s56, s60
	s_cselect_b32 s37, s21, s61
	s_add_u32 s30, s38, 0x80
	s_addc_u32 s31, s39, 0
	s_add_i32 m0, s43, 0xc000
	ds_read_b128 v[174:177], v139
	ds_read_b128 v[178:181], v139 offset:1024
	ds_read_b128 v[182:185], v139 offset:2048
	ds_read_b128 v[186:189], v139 offset:3072
	ds_read_b128 v[190:193], v139 offset:4096
	ds_read_b128 v[194:197], v139 offset:5120
	ds_read_b128 v[198:201], v139 offset:6144
	ds_read_b128 v[202:205], v139 offset:7168
	global_load_lds_dwordx4 v128, s[28:29]
	s_add_i32 m0, s43, 0xe000
	s_nop 0
	global_load_lds_dwordx4 v130, s[28:29]
	s_waitcnt vmcnt(8) lgkmcnt(0)
	s_barrier
	v_mfma_scale_f32_16x16x128_f8f6f4 v[124:127], v[142:149], v[174:181], v[124:127], v140, v140 op_sel_hi:[0,0,0]
	v_mfma_scale_f32_16x16x128_f8f6f4 v[120:123], v[150:157], v[174:181], v[120:123], v140, v140 op_sel_hi:[0,0,0]
	v_mfma_scale_f32_16x16x128_f8f6f4 v[112:115], v[142:149], v[182:189], v[112:115], v140, v140 op_sel_hi:[0,0,0]
	v_mfma_scale_f32_16x16x128_f8f6f4 v[104:107], v[150:157], v[182:189], v[104:107], v140, v140 op_sel_hi:[0,0,0]
	v_mfma_scale_f32_16x16x128_f8f6f4 v[96:99], v[142:149], v[190:197], v[96:99], v140, v140 op_sel_hi:[0,0,0]
	v_mfma_scale_f32_16x16x128_f8f6f4 v[206:209], v[150:157], v[190:197], v[88:91], v140, v140 op_sel_hi:[0,0,0]
	v_mfma_scale_f32_16x16x128_f8f6f4 v[210:213], v[142:149], v[198:205], v[80:83], v140, v140 op_sel_hi:[0,0,0]
	v_mfma_scale_f32_16x16x128_f8f6f4 v[214:217], v[150:157], v[198:205], v[72:75], v140, v140 op_sel_hi:[0,0,0]
	v_mfma_scale_f32_16x16x128_f8f6f4 v[116:119], v[158:165], v[174:181], v[116:119], v140, v140 op_sel_hi:[0,0,0]
	v_mfma_scale_f32_16x16x128_f8f6f4 v[108:111], v[166:173], v[174:181], v[108:111], v140, v140 op_sel_hi:[0,0,0]
	v_mfma_scale_f32_16x16x128_f8f6f4 v[100:103], v[158:165], v[182:189], v[100:103], v140, v140 op_sel_hi:[0,0,0]
	v_mfma_scale_f32_16x16x128_f8f6f4 v[174:177], v[166:173], v[182:189], v[92:95], v140, v140 op_sel_hi:[0,0,0]
	v_mfma_scale_f32_16x16x128_f8f6f4 v[178:181], v[158:165], v[190:197], v[84:87], v140, v140 op_sel_hi:[0,0,0]
	v_mfma_scale_f32_16x16x128_f8f6f4 v[182:185], v[166:173], v[190:197], v[76:79], v140, v140 op_sel_hi:[0,0,0]
	v_mfma_scale_f32_16x16x128_f8f6f4 v[186:189], v[158:165], v[198:205], v[68:71], v140, v140 op_sel_hi:[0,0,0]
	v_mfma_scale_f32_16x16x128_f8f6f4 v[190:193], v[166:173], v[198:205], v[64:67], v140, v140 op_sel_hi:[0,0,0]
	s_barrier
	s_add_i32 s63, s53, s41
	s_mov_b32 m0, s63
	s_nop 1
	ds_read_b128 v[64:67], v139 offset:16384
	ds_read_b128 v[68:71], v139 offset:17408
	ds_read_b128 v[72:75], v139 offset:18432
	ds_read_b128 v[76:79], v139 offset:19456
	ds_read_b128 v[80:83], v139 offset:20480
	ds_read_b128 v[84:87], v139 offset:21504
	ds_read_b128 v[88:91], v139 offset:22528
	ds_read_b128 v[92:95], v139 offset:23552
	global_load_lds_dwordx4 v128, s[36:37]
	s_add_i32 m0, s63, 0x2000
	s_add_u32 s64, s36, 0x80000
	s_addc_u32 s65, s37, 0
	s_add_i32 s63, s54, s41
	global_load_lds_dwordx4 v130, s[36:37]
	s_mov_b32 m0, s63
	s_nop 0
	global_load_lds_dwordx4 v128, s[64:65]
	s_add_i32 m0, s63, 0x2000
	s_nop 0
	global_load_lds_dwordx4 v130, s[64:65]
	s_waitcnt vmcnt(4) lgkmcnt(0)
	s_barrier
	v_mfma_scale_f32_16x16x128_f8f6f4 v[60:63], v[142:149], v[64:71], v[60:63], v140, v140 op_sel_hi:[0,0,0]
	v_mfma_scale_f32_16x16x128_f8f6f4 v[56:59], v[150:157], v[64:71], v[56:59], v140, v140 op_sel_hi:[0,0,0]
	v_mfma_scale_f32_16x16x128_f8f6f4 v[48:51], v[142:149], v[72:79], v[48:51], v140, v140 op_sel_hi:[0,0,0]
	v_mfma_scale_f32_16x16x128_f8f6f4 v[194:197], v[150:157], v[72:79], v[40:43], v140, v140 op_sel_hi:[0,0,0]
	v_mfma_scale_f32_16x16x128_f8f6f4 v[198:201], v[142:149], v[80:87], v[32:35], v140, v140 op_sel_hi:[0,0,0]
	v_mfma_scale_f32_16x16x128_f8f6f4 v[202:205], v[150:157], v[80:87], v[24:27], v140, v140 op_sel_hi:[0,0,0]
	v_mfma_scale_f32_16x16x128_f8f6f4 v[218:221], v[142:149], v[88:95], v[16:19], v140, v140 op_sel_hi:[0,0,0]
	v_mfma_scale_f32_16x16x128_f8f6f4 v[222:225], v[150:157], v[88:95], v[8:11], v140, v140 op_sel_hi:[0,0,0]
	v_mfma_scale_f32_16x16x128_f8f6f4 v[52:55], v[158:165], v[64:71], v[52:55], v140, v140 op_sel_hi:[0,0,0]
	v_mfma_scale_f32_16x16x128_f8f6f4 v[226:229], v[166:173], v[64:71], v[44:47], v140, v140 op_sel_hi:[0,0,0]
	v_mfma_scale_f32_16x16x128_f8f6f4 v[230:233], v[158:165], v[72:79], v[36:39], v140, v140 op_sel_hi:[0,0,0]
	v_mfma_scale_f32_16x16x128_f8f6f4 v[234:237], v[166:173], v[72:79], v[28:31], v140, v140 op_sel_hi:[0,0,0]
	v_mfma_scale_f32_16x16x128_f8f6f4 v[238:241], v[158:165], v[80:87], v[20:23], v140, v140 op_sel_hi:[0,0,0]
	v_mfma_scale_f32_16x16x128_f8f6f4 v[242:245], v[166:173], v[80:87], v[12:15], v140, v140 op_sel_hi:[0,0,0]
	v_mfma_scale_f32_16x16x128_f8f6f4 v[246:249], v[158:165], v[88:95], v[4:7], v140, v140 op_sel_hi:[0,0,0]
	v_mfma_scale_f32_16x16x128_f8f6f4 v[250:253], v[166:173], v[88:95], v[0:3], v140, v140 op_sel_hi:[0,0,0]
	s_barrier
; #define PG8_WAIT_V(n) asm volatile("s_waitcnt vmcnt(" #n ")" ::: "memory")
; #define PG8_WAIT_L(n) asm volatile("s_waitcnt lgkmcnt(" #n ")" ::: "memory")
; #define PG8_BAR __builtin_amdgcn_s_barrier()
; #define PG8_SCHED __builtin_amdgcn_sched_barrier(0)
;     ...
;         for (int t = 0; t < nt; t += 2) {
;     ...
;             PG8_LDB(B0, 1, 0); PG8_LDB(B1, 1, 1); PG8_SCHED; PG8_LDA(At, 1, 0); PG8_STAGE(PG8_SA(0, 1), a2 + hstepA, voffA);
;             PG8_WAIT_V(8); PG8_WAIT_L(0); PG8_BAR; PG8_MMA(0, 0, At, B0); PG8_MMA(0, 1, At, B1); PG8_BAR; PG8_SCHED;
;             if constexpr (!HALFU) PG8_LDA(At, 1, 1); PG8_STAGE(PG8_SB(1, 0), b3, voffB); PG8_STAGE(PG8_SB(1, 1), b3 + hstep, voffB); PG8_STAGE(PG8_SA(1, 0), a3, voffA);
;             PG8_WAIT_V(8); PG8_WAIT_L(0); PG8_BAR; if constexpr (!HALFU) { PG8_MMA(1, 0, At, B0); PG8_MMA(1, 1, At, B1); } PG8_BAR; PG8_SCHED;
	s_mov_b32 m0, s43
	s_nop 0
	global_load_lds_dwordx4 v128, s[38:39]
	s_mov_b32 m0, s44
	s_nop 0
	global_load_lds_dwordx4 v130, s[38:39]
	s_add_i32 s63, 0, 0x18000
	s_add_i32 s64, 0, 0x1c000
	s_nop 0
	v_add_u32_e32 v12, s63, v136
	v_add_u32_e32 v16, s64, v136
	ds_read_b128 v[0:3], v12
	ds_read_b128 v[4:7], v12 offset:1024
	ds_read_b128 v[8:11], v12 offset:2048
	ds_read_b128 v[12:15], v12 offset:3072
	ds_read_b128 v[142:145], v16
	ds_read_b128 v[146:149], v16 offset:1024
	ds_read_b128 v[150:153], v16 offset:2048
	ds_read_b128 v[154:157], v16 offset:3072
	s_add_u32 s38, s38, 0x80000
	s_addc_u32 s39, s39, 0
	s_mov_b32 m0, s45
	ds_read_b128 v[16:19], v139 offset:32768
	ds_read_b128 v[20:23], v139 offset:33792
	ds_read_b128 v[24:27], v139 offset:34816
	ds_read_b128 v[28:31], v139 offset:35840
	ds_read_b128 v[32:35], v139 offset:36864
	ds_read_b128 v[36:39], v139 offset:37888
	ds_read_b128 v[40:43], v139 offset:38912
	ds_read_b128 v[44:47], v139 offset:39936
	global_load_lds_dwordx4 v128, s[38:39]
	s_mov_b32 m0, s46
	s_nop 0
	global_load_lds_dwordx4 v130, s[38:39]
	s_waitcnt vmcnt(8) lgkmcnt(0)
	s_barrier
	v_mfma_scale_f32_16x16x128_f8f6f4 v[124:127], v[0:7], v[16:23], v[124:127], v140, v140 op_sel_hi:[0,0,0]
	v_mfma_scale_f32_16x16x128_f8f6f4 v[120:123], v[8:15], v[16:23], v[120:123], v140, v140 op_sel_hi:[0,0,0]
	v_mfma_scale_f32_16x16x128_f8f6f4 v[112:115], v[0:7], v[24:31], v[112:115], v140, v140 op_sel_hi:[0,0,0]
	v_mfma_scale_f32_16x16x128_f8f6f4 v[104:107], v[8:15], v[24:31], v[104:107], v140, v140 op_sel_hi:[0,0,0]
	v_mfma_scale_f32_16x16x128_f8f6f4 v[96:99], v[0:7], v[32:39], v[96:99], v140, v140 op_sel_hi:[0,0,0]
	v_mfma_scale_f32_16x16x128_f8f6f4 v[88:91], v[8:15], v[32:39], v[206:209], v140, v140 op_sel_hi:[0,0,0]
	v_mfma_scale_f32_16x16x128_f8f6f4 v[80:83], v[0:7], v[40:47], v[210:213], v140, v140 op_sel_hi:[0,0,0]
	v_mfma_scale_f32_16x16x128_f8f6f4 v[72:75], v[8:15], v[40:47], v[214:217], v140, v140 op_sel_hi:[0,0,0]
	v_mfma_scale_f32_16x16x128_f8f6f4 v[116:119], v[142:149], v[16:23], v[116:119], v140, v140 op_sel_hi:[0,0,0]
	v_mfma_scale_f32_16x16x128_f8f6f4 v[108:111], v[150:157], v[16:23], v[108:111], v140, v140 op_sel_hi:[0,0,0]
	v_mfma_scale_f32_16x16x128_f8f6f4 v[100:103], v[142:149], v[24:31], v[100:103], v140, v140 op_sel_hi:[0,0,0]
	v_mfma_scale_f32_16x16x128_f8f6f4 v[92:95], v[150:157], v[24:31], v[174:177], v140, v140 op_sel_hi:[0,0,0]
	v_mfma_scale_f32_16x16x128_f8f6f4 v[84:87], v[142:149], v[32:39], v[178:181], v140, v140 op_sel_hi:[0,0,0]
	v_mfma_scale_f32_16x16x128_f8f6f4 v[76:79], v[150:157], v[32:39], v[182:185], v140, v140 op_sel_hi:[0,0,0]
	v_mfma_scale_f32_16x16x128_f8f6f4 v[68:71], v[142:149], v[40:47], v[186:189], v140, v140 op_sel_hi:[0,0,0]
	v_mfma_scale_f32_16x16x128_f8f6f4 v[64:67], v[150:157], v[40:47], v[190:193], v140, v140 op_sel_hi:[0,0,0]
	s_barrier
	s_add_u32 s38, s36, 0x80
	s_addc_u32 s39, s37, 0
	s_add_i32 s63, s63, s41
	s_mov_b32 m0, s63
	ds_read_b128 v[158:161], v139 offset:49152
	ds_read_b128 v[162:165], v139 offset:50176
	ds_read_b128 v[166:169], v139 offset:51200
	ds_read_b128 v[170:173], v139 offset:52224
	ds_read_b128 v[174:177], v139 offset:53248
	ds_read_b128 v[178:181], v139 offset:54272
	ds_read_b128 v[182:185], v139 offset:55296
	ds_read_b128 v[186:189], v139 offset:56320
	global_load_lds_dwordx4 v128, s[38:39]
	s_add_i32 m0, s63, 0x2000
	s_add_u32 s36, s36, 0x80080
	v_lshl_add_u64 v[16:17], s[38:39], 0, v[130:131]
	s_addc_u32 s37, s37, 0
	s_add_i32 s38, s64, s41
	global_load_lds_dwordx4 v[16:17], off
	s_mov_b32 m0, s38
	s_nop 0
	global_load_lds_dwordx4 v128, s[36:37]
	s_add_i32 m0, s38, 0x2000
	s_nop 0
	global_load_lds_dwordx4 v130, s[36:37]
	s_waitcnt vmcnt(4) lgkmcnt(0)
	s_barrier
	v_mfma_scale_f32_16x16x128_f8f6f4 v[60:63], v[0:7], v[158:165], v[60:63], v140, v140 op_sel_hi:[0,0,0]
	v_mfma_scale_f32_16x16x128_f8f6f4 v[56:59], v[8:15], v[158:165], v[56:59], v140, v140 op_sel_hi:[0,0,0]
	v_mfma_scale_f32_16x16x128_f8f6f4 v[48:51], v[0:7], v[166:173], v[48:51], v140, v140 op_sel_hi:[0,0,0]
	v_mfma_scale_f32_16x16x128_f8f6f4 v[40:43], v[8:15], v[166:173], v[194:197], v140, v140 op_sel_hi:[0,0,0]
	v_mfma_scale_f32_16x16x128_f8f6f4 v[32:35], v[0:7], v[174:181], v[198:201], v140, v140 op_sel_hi:[0,0,0]
	v_mfma_scale_f32_16x16x128_f8f6f4 v[24:27], v[8:15], v[174:181], v[202:205], v140, v140 op_sel_hi:[0,0,0]
	v_mfma_scale_f32_16x16x128_f8f6f4 v[16:19], v[0:7], v[182:189], v[218:221], v140, v140 op_sel_hi:[0,0,0]
	v_mfma_scale_f32_16x16x128_f8f6f4 v[8:11], v[8:15], v[182:189], v[222:225], v140, v140 op_sel_hi:[0,0,0]
	v_mfma_scale_f32_16x16x128_f8f6f4 v[52:55], v[142:149], v[158:165], v[52:55], v140, v140 op_sel_hi:[0,0,0]
	v_mfma_scale_f32_16x16x128_f8f6f4 v[44:47], v[150:157], v[158:165], v[226:229], v140, v140 op_sel_hi:[0,0,0]
	v_mfma_scale_f32_16x16x128_f8f6f4 v[36:39], v[142:149], v[166:173], v[230:233], v140, v140 op_sel_hi:[0,0,0]
	v_mfma_scale_f32_16x16x128_f8f6f4 v[28:31], v[150:157], v[166:173], v[234:237], v140, v140 op_sel_hi:[0,0,0]
	v_mfma_scale_f32_16x16x128_f8f6f4 v[20:23], v[142:149], v[174:181], v[238:241], v140, v140 op_sel_hi:[0,0,0]
	v_mfma_scale_f32_16x16x128_f8f6f4 v[12:15], v[150:157], v[174:181], v[242:245], v140, v140 op_sel_hi:[0,0,0]
	v_mfma_scale_f32_16x16x128_f8f6f4 v[4:7], v[142:149], v[182:189], v[246:249], v140, v140 op_sel_hi:[0,0,0]
	v_mfma_scale_f32_16x16x128_f8f6f4 v[0:3], v[150:157], v[182:189], v[250:253], v140, v140 op_sel_hi:[0,0,0]
	s_barrier
	s_add_i32 s62, s62, 2
	s_add_u32 s57, s57, 0x100
	s_addc_u32 s59, s59, 0
	s_add_u32 s60, s60, 0x100
	s_addc_u32 s61, s61, 0
	s_add_u32 s28, s28, 0x100
	s_addc_u32 s29, s29, 0
	s_cmp_gt_u32 s62, 29
	s_cbranch_scc0 .LBB0_3426
	s_and_b64 vcc, exec, s[6:7]
	s_cbranch_vccz .LBB0_3429
	s_barrier

; #define PG8_WAIT_V(n) asm volatile("s_waitcnt vmcnt(" #n ")" ::: "memory")
; #define PG8_WAIT_L(n) asm volatile("s_waitcnt lgkmcnt(" #n ")" ::: "memory")
; #define PG8_BAR __builtin_amdgcn_s_barrier()
; #define PG8_SCHED __builtin_amdgcn_sched_barrier(0)
;     ...
;             const char* a1 = cA + (size_t)(t + 1) * kstep;
;             const char* a2 = last ? nA : cA + (size_t)(t + 2) * kstep; const char* b2 = last ? nB : cB + (size_t)(t + 2) * kstep;
;             const char* a3 = a2 + kstep; const char* b3 = b2 + kstep;
;             if (last && has_next) S.a_ready(nxt);
;             if constexpr (SP2) {
;             PG8_LDB(B0, 0, 0); PG8_LDB(B1, 0, 1); PG8_SCHED; PG8_LDA(At, 0, 0); PG8_STAGE(PG8_SA(1, 1), a1 + hstepA, voffA);
;             PG8_WAIT_V(8); PG8_WAIT_L(0); PG8_BAR; PG8_MMA(0, 0, At, B0); PG8_MMA(0, 1, At, B1); PG8_BAR; PG8_SCHED;
;             if constexpr (!HALFU) PG8_LDA(At, 0, 1); PG8_STAGE(PG8_SB(0, 0), b2, voffB); PG8_STAGE(PG8_SB(0, 1), b2 + hstep, voffB); PG8_STAGE(PG8_SA(0, 0), a2, voffA);
;             PG8_WAIT_V(8); PG8_WAIT_L(0); PG8_BAR; if constexpr (!HALFU) { PG8_MMA(1, 0, At, B0); PG8_MMA(1, 1, At, B1); } PG8_BAR; PG8_SCHED;
.LBB0_3554:
	s_add_u32 s98, s24, 0x80
	s_addc_u32 s99, s25, 0
	s_mov_b32 m0, s49
	s_nop 0
	global_load_lds_dwordx4 v134, s[98:99]
	s_mov_b32 m0, s50
	s_nop 0
	global_load_lds_dwordx4 v132, s[98:99]
	ds_read_b128 v[144:147], v141
	ds_read_b128 v[148:151], v141 offset:1024
	ds_read_b128 v[152:155], v141 offset:2048
	ds_read_b128 v[156:159], v141 offset:3072
	ds_read_b128 v[160:163], v142
	ds_read_b128 v[164:167], v142 offset:1024
	ds_read_b128 v[168:171], v142 offset:2048
	ds_read_b128 v[172:175], v142 offset:3072
	s_add_u32 s26, s24, 0x100
	s_addc_u32 s27, s25, 0
	s_cmp_eq_u32 s59, 60
	s_cselect_b32 s36, s54, s26
	s_cselect_b32 s37, s15, s27
	s_cselect_b32 s30, s55, s56
	s_cselect_b32 s31, s13, s57
	s_add_u32 s28, s36, 0x80
	s_addc_u32 s29, s37, 0
	s_add_u32 s24, s24, 0x100080
	s_addc_u32 s25, s25, 0
	s_add_i32 m0, s23, 0xc000
	ds_read_b128 v[176:179], v143
	ds_read_b128 v[180:183], v143 offset:1024
	ds_read_b128 v[184:187], v143 offset:2048
	ds_read_b128 v[188:191], v143 offset:3072
	ds_read_b128 v[192:195], v143 offset:4096
	ds_read_b128 v[196:199], v143 offset:5120
	ds_read_b128 v[200:203], v143 offset:6144
	ds_read_b128 v[204:207], v143 offset:7168
	global_load_lds_dwordx4 v134, s[24:25]
	s_add_i32 m0, s23, 0xe000
	s_nop 0
	global_load_lds_dwordx4 v132, s[24:25]
	s_waitcnt vmcnt(8) lgkmcnt(0)
	s_barrier
	v_mfma_f32_16x16x32_bf16 v[124:127], v[144:147], v[176:179], v[124:127]
	v_mfma_f32_16x16x32_bf16 v[120:123], v[152:155], v[176:179], v[120:123]
	v_mfma_f32_16x16x32_bf16 v[108:111], v[144:147], v[184:187], v[108:111]
	v_mfma_f32_16x16x32_bf16 v[104:107], v[152:155], v[184:187], v[104:107]
	v_mfma_f32_16x16x32_bf16 v[92:95], v[144:147], v[192:195], v[92:95]
	v_mfma_f32_16x16x32_bf16 v[88:91], v[152:155], v[192:195], v[88:91]
	v_mfma_f32_16x16x32_bf16 v[76:79], v[144:147], v[200:203], v[76:79]
	v_mfma_f32_16x16x32_bf16 v[72:75], v[152:155], v[200:203], v[72:75]
	v_mfma_f32_16x16x32_bf16 v[124:127], v[148:151], v[180:183], v[124:127]
	v_mfma_f32_16x16x32_bf16 v[120:123], v[156:159], v[180:183], v[120:123]
	v_mfma_f32_16x16x32_bf16 v[108:111], v[148:151], v[188:191], v[108:111]
	v_mfma_f32_16x16x32_bf16 v[104:107], v[156:159], v[188:191], v[104:107]
	v_mfma_f32_16x16x32_bf16 v[92:95], v[148:151], v[196:199], v[92:95]
	v_mfma_f32_16x16x32_bf16 v[88:91], v[156:159], v[196:199], v[88:91]
	v_mfma_f32_16x16x32_bf16 v[76:79], v[148:151], v[204:207], v[76:79]
	v_mfma_f32_16x16x32_bf16 v[72:75], v[156:159], v[204:207], v[72:75]
	v_mfma_f32_16x16x32_bf16 v[116:119], v[160:163], v[176:179], v[116:119]
	v_mfma_f32_16x16x32_bf16 v[112:115], v[168:171], v[176:179], v[112:115]
	v_mfma_f32_16x16x32_bf16 v[100:103], v[160:163], v[184:187], v[100:103]
	v_mfma_f32_16x16x32_bf16 v[96:99], v[168:171], v[184:187], v[96:99]
	v_mfma_f32_16x16x32_bf16 v[84:87], v[160:163], v[192:195], v[84:87]
	v_mfma_f32_16x16x32_bf16 v[80:83], v[168:171], v[192:195], v[80:83]
	v_mfma_f32_16x16x32_bf16 v[68:71], v[160:163], v[200:203], v[68:71]
	v_mfma_f32_16x16x32_bf16 v[64:67], v[168:171], v[200:203], v[64:67]
	v_mfma_f32_16x16x32_bf16 v[116:119], v[164:167], v[180:183], v[116:119]
	v_mfma_f32_16x16x32_bf16 v[112:115], v[172:175], v[180:183], v[112:115]
	v_mfma_f32_16x16x32_bf16 v[100:103], v[164:167], v[188:191], v[100:103]
	v_mfma_f32_16x16x32_bf16 v[96:99], v[172:175], v[188:191], v[96:99]
	v_mfma_f32_16x16x32_bf16 v[84:87], v[164:167], v[196:199], v[84:87]
	v_mfma_f32_16x16x32_bf16 v[80:83], v[172:175], v[196:199], v[80:83]
	v_mfma_f32_16x16x32_bf16 v[68:71], v[164:167], v[204:207], v[68:71]
	v_mfma_f32_16x16x32_bf16 v[64:67], v[172:175], v[204:207], v[64:67]
	s_barrier
	s_add_i32 s24, s6, s40
	s_mov_b32 m0, s24
	ds_read_b128 v[176:179], v143 offset:16384
	ds_read_b128 v[180:183], v143 offset:17408
	ds_read_b128 v[184:187], v143 offset:18432
	ds_read_b128 v[188:191], v143 offset:19456
	ds_read_b128 v[192:195], v143 offset:20480
	ds_read_b128 v[196:199], v143 offset:21504
	ds_read_b128 v[200:203], v143 offset:22528
	ds_read_b128 v[204:207], v143 offset:23552
	global_load_lds_dwordx4 v128, s[30:31]
	s_add_i32 m0, s24, 0x2000
	s_add_u32 s24, s30, 0x100000
	s_addc_u32 s25, s31, 0
	s_add_i32 s60, s51, s40
	global_load_lds_dwordx4 v130, s[30:31]
	s_mov_b32 m0, s60
	s_nop 0
	global_load_lds_dwordx4 v128, s[24:25]
	s_add_i32 m0, s60, 0x2000
	s_nop 0
	global_load_lds_dwordx4 v130, s[24:25]
	s_waitcnt vmcnt(4) lgkmcnt(0)
	s_barrier
	v_mfma_f32_16x16x32_bf16 v[60:63], v[144:147], v[176:179], v[60:63]
	v_mfma_f32_16x16x32_bf16 v[56:59], v[152:155], v[176:179], v[56:59]
	v_mfma_f32_16x16x32_bf16 v[44:47], v[144:147], v[184:187], v[44:47]
	v_mfma_f32_16x16x32_bf16 v[40:43], v[152:155], v[184:187], v[40:43]
	v_mfma_f32_16x16x32_bf16 v[28:31], v[144:147], v[192:195], v[28:31]
	v_mfma_f32_16x16x32_bf16 v[24:27], v[152:155], v[192:195], v[24:27]
	v_mfma_f32_16x16x32_bf16 v[12:15], v[144:147], v[200:203], v[12:15]
	v_mfma_f32_16x16x32_bf16 v[8:11], v[152:155], v[200:203], v[8:11]
	v_mfma_f32_16x16x32_bf16 v[60:63], v[148:151], v[180:183], v[60:63]
	v_mfma_f32_16x16x32_bf16 v[56:59], v[156:159], v[180:183], v[56:59]
	v_mfma_f32_16x16x32_bf16 v[44:47], v[148:151], v[188:191], v[44:47]
	v_mfma_f32_16x16x32_bf16 v[40:43], v[156:159], v[188:191], v[40:43]
	v_mfma_f32_16x16x32_bf16 v[28:31], v[148:151], v[196:199], v[28:31]
	v_mfma_f32_16x16x32_bf16 v[24:27], v[156:159], v[196:199], v[24:27]
	v_mfma_f32_16x16x32_bf16 v[12:15], v[148:151], v[204:207], v[12:15]
	v_mfma_f32_16x16x32_bf16 v[8:11], v[156:159], v[204:207], v[8:11]
	v_mfma_f32_16x16x32_bf16 v[52:55], v[160:163], v[176:179], v[52:55]
	v_mfma_f32_16x16x32_bf16 v[48:51], v[168:171], v[176:179], v[48:51]
	v_mfma_f32_16x16x32_bf16 v[36:39], v[160:163], v[184:187], v[36:39]
	v_mfma_f32_16x16x32_bf16 v[32:35], v[168:171], v[184:187], v[32:35]
	v_mfma_f32_16x16x32_bf16 v[20:23], v[160:163], v[192:195], v[20:23]
	v_mfma_f32_16x16x32_bf16 v[16:19], v[168:171], v[192:195], v[16:19]
	v_mfma_f32_16x16x32_bf16 v[4:7], v[160:163], v[200:203], v[4:7]
	v_mfma_f32_16x16x32_bf16 v[0:3], v[168:171], v[200:203], v[0:3]
	v_mfma_f32_16x16x32_bf16 v[52:55], v[164:167], v[180:183], v[52:55]
	v_mfma_f32_16x16x32_bf16 v[48:51], v[172:175], v[180:183], v[48:51]
	v_mfma_f32_16x16x32_bf16 v[36:39], v[164:167], v[188:191], v[36:39]
	v_mfma_f32_16x16x32_bf16 v[32:35], v[172:175], v[188:191], v[32:35]
	v_mfma_f32_16x16x32_bf16 v[20:23], v[164:167], v[196:199], v[20:23]
	v_mfma_f32_16x16x32_bf16 v[16:19], v[172:175], v[196:199], v[16:19]
	v_mfma_f32_16x16x32_bf16 v[4:7], v[164:167], v[204:207], v[4:7]
	v_mfma_f32_16x16x32_bf16 v[0:3], v[172:175], v[204:207], v[0:3]
	s_barrier
; #define PG8_WAIT_V(n) asm volatile("s_waitcnt vmcnt(" #n ")" ::: "memory")
; #define PG8_WAIT_L(n) asm volatile("s_waitcnt lgkmcnt(" #n ")" ::: "memory")
; #define PG8_BAR __builtin_amdgcn_s_barrier()
; #define PG8_SCHED __builtin_amdgcn_sched_barrier(0)
;     ...
;         for (int t = 0; t < nt; t += 2) {
;     ...
;             PG8_LDB(B0, 1, 0); PG8_LDB(B1, 1, 1); PG8_SCHED; PG8_LDA(At, 1, 0); PG8_STAGE(PG8_SA(0, 1), a2 + hstepA, voffA);
;             PG8_WAIT_V(8); PG8_WAIT_L(0); PG8_BAR; PG8_MMA(0, 0, At, B0); PG8_MMA(0, 1, At, B1); PG8_BAR; PG8_SCHED;
;             if constexpr (!HALFU) PG8_LDA(At, 1, 1); PG8_STAGE(PG8_SB(1, 0), b3, voffB); PG8_STAGE(PG8_SB(1, 1), b3 + hstep, voffB); PG8_STAGE(PG8_SA(1, 0), a3, voffA);
;             PG8_WAIT_V(8); PG8_WAIT_L(0); PG8_BAR; if constexpr (!HALFU) { PG8_MMA(1, 0, At, B0); PG8_MMA(1, 1, At, B1); } PG8_BAR; PG8_SCHED;
	s_mov_b32 m0, s23
	s_nop 0
	global_load_lds_dwordx4 v134, s[36:37]
	s_mov_b32 m0, s43
	s_nop 0
	global_load_lds_dwordx4 v132, s[36:37]
	s_add_i32 s60, 0, 0x18000
	v_add_u32_e32 v138, s60, v140
	s_add_i32 s61, 0, 0x1c000
	ds_read_b128 v[144:147], v138
	ds_read_b128 v[148:151], v138 offset:1024
	ds_read_b128 v[152:155], v138 offset:2048
	ds_read_b128 v[156:159], v138 offset:3072
	v_add_u32_e32 v138, s61, v140
	ds_read_b128 v[160:163], v138
	ds_read_b128 v[164:167], v138 offset:1024
	ds_read_b128 v[168:171], v138 offset:2048
	ds_read_b128 v[172:175], v138 offset:3072
	s_add_u32 s24, s36, 0x100000
	s_addc_u32 s25, s37, 0
	s_mov_b32 m0, s44
	ds_read_b128 v[176:179], v143 offset:32768
	ds_read_b128 v[180:183], v143 offset:33792
	ds_read_b128 v[184:187], v143 offset:34816
	ds_read_b128 v[188:191], v143 offset:35840
	ds_read_b128 v[192:195], v143 offset:36864
	ds_read_b128 v[196:199], v143 offset:37888
	ds_read_b128 v[200:203], v143 offset:38912
	ds_read_b128 v[204:207], v143 offset:39936
	global_load_lds_dwordx4 v134, s[24:25]
	s_mov_b32 m0, s45
	s_nop 0
	global_load_lds_dwordx4 v132, s[24:25]
	s_waitcnt vmcnt(8) lgkmcnt(0)
	s_barrier
	v_mfma_f32_16x16x32_bf16 v[124:127], v[144:147], v[176:179], v[124:127]
	v_mfma_f32_16x16x32_bf16 v[120:123], v[152:155], v[176:179], v[120:123]
	v_mfma_f32_16x16x32_bf16 v[108:111], v[144:147], v[184:187], v[108:111]
	v_mfma_f32_16x16x32_bf16 v[104:107], v[152:155], v[184:187], v[104:107]
	v_mfma_f32_16x16x32_bf16 v[92:95], v[144:147], v[192:195], v[92:95]
	v_mfma_f32_16x16x32_bf16 v[88:91], v[152:155], v[192:195], v[88:91]
	v_mfma_f32_16x16x32_bf16 v[76:79], v[144:147], v[200:203], v[76:79]
	v_mfma_f32_16x16x32_bf16 v[72:75], v[152:155], v[200:203], v[72:75]
	v_mfma_f32_16x16x32_bf16 v[124:127], v[148:151], v[180:183], v[124:127]
	v_mfma_f32_16x16x32_bf16 v[120:123], v[156:159], v[180:183], v[120:123]
	v_mfma_f32_16x16x32_bf16 v[108:111], v[148:151], v[188:191], v[108:111]
	v_mfma_f32_16x16x32_bf16 v[104:107], v[156:159], v[188:191], v[104:107]
	v_mfma_f32_16x16x32_bf16 v[92:95], v[148:151], v[196:199], v[92:95]
	v_mfma_f32_16x16x32_bf16 v[88:91], v[156:159], v[196:199], v[88:91]
	v_mfma_f32_16x16x32_bf16 v[76:79], v[148:151], v[204:207], v[76:79]
	v_mfma_f32_16x16x32_bf16 v[72:75], v[156:159], v[204:207], v[72:75]
	v_mfma_f32_16x16x32_bf16 v[116:119], v[160:163], v[176:179], v[116:119]
	v_mfma_f32_16x16x32_bf16 v[112:115], v[168:171], v[176:179], v[112:115]
	v_mfma_f32_16x16x32_bf16 v[100:103], v[160:163], v[184:187], v[100:103]
	v_mfma_f32_16x16x32_bf16 v[96:99], v[168:171], v[184:187], v[96:99]
	v_mfma_f32_16x16x32_bf16 v[84:87], v[160:163], v[192:195], v[84:87]
	v_mfma_f32_16x16x32_bf16 v[80:83], v[168:171], v[192:195], v[80:83]
	v_mfma_f32_16x16x32_bf16 v[68:71], v[160:163], v[200:203], v[68:71]
	v_mfma_f32_16x16x32_bf16 v[64:67], v[168:171], v[200:203], v[64:67]
	v_mfma_f32_16x16x32_bf16 v[116:119], v[164:167], v[180:183], v[116:119]
	v_mfma_f32_16x16x32_bf16 v[112:115], v[172:175], v[180:183], v[112:115]
	v_mfma_f32_16x16x32_bf16 v[100:103], v[164:167], v[188:191], v[100:103]
	v_mfma_f32_16x16x32_bf16 v[96:99], v[172:175], v[188:191], v[96:99]
	v_mfma_f32_16x16x32_bf16 v[84:87], v[164:167], v[196:199], v[84:87]
	v_mfma_f32_16x16x32_bf16 v[80:83], v[172:175], v[196:199], v[80:83]
	v_mfma_f32_16x16x32_bf16 v[68:71], v[164:167], v[204:207], v[68:71]
	v_mfma_f32_16x16x32_bf16 v[64:67], v[172:175], v[204:207], v[64:67]
	s_barrier
	s_add_u32 s24, s30, 0x80
	s_addc_u32 s25, s31, 0
	s_add_i32 s36, s60, s40
	s_mov_b32 m0, s36
	ds_read_b128 v[176:179], v143 offset:49152
	ds_read_b128 v[180:183], v143 offset:50176
	ds_read_b128 v[184:187], v143 offset:51200
	ds_read_b128 v[188:191], v143 offset:52224
	ds_read_b128 v[192:195], v143 offset:53248
	ds_read_b128 v[196:199], v143 offset:54272
	ds_read_b128 v[200:203], v143 offset:55296
	ds_read_b128 v[204:207], v143 offset:56320
	global_load_lds_dwordx4 v128, s[24:25]
	s_add_i32 m0, s36, 0x2000
	v_lshl_add_u64 v[138:139], s[24:25], 0, v[130:131]
	s_add_u32 s24, s30, 0x100080
	s_addc_u32 s25, s31, 0
	s_add_i32 s30, s61, s40
	global_load_lds_dwordx4 v[138:139], off
	s_mov_b32 m0, s30
	s_nop 0
	global_load_lds_dwordx4 v128, s[24:25]
	s_add_i32 m0, s30, 0x2000
	s_nop 0
	global_load_lds_dwordx4 v130, s[24:25]
	s_waitcnt vmcnt(4) lgkmcnt(0)
	s_barrier
	v_mfma_f32_16x16x32_bf16 v[60:63], v[144:147], v[176:179], v[60:63]
	v_mfma_f32_16x16x32_bf16 v[56:59], v[152:155], v[176:179], v[56:59]
	v_mfma_f32_16x16x32_bf16 v[44:47], v[144:147], v[184:187], v[44:47]
	v_mfma_f32_16x16x32_bf16 v[40:43], v[152:155], v[184:187], v[40:43]
	v_mfma_f32_16x16x32_bf16 v[28:31], v[144:147], v[192:195], v[28:31]
	v_mfma_f32_16x16x32_bf16 v[24:27], v[152:155], v[192:195], v[24:27]
	v_mfma_f32_16x16x32_bf16 v[12:15], v[144:147], v[200:203], v[12:15]
	v_mfma_f32_16x16x32_bf16 v[8:11], v[152:155], v[200:203], v[8:11]
	v_mfma_f32_16x16x32_bf16 v[60:63], v[148:151], v[180:183], v[60:63]
	v_mfma_f32_16x16x32_bf16 v[56:59], v[156:159], v[180:183], v[56:59]
	v_mfma_f32_16x16x32_bf16 v[44:47], v[148:151], v[188:191], v[44:47]
	v_mfma_f32_16x16x32_bf16 v[40:43], v[156:159], v[188:191], v[40:43]
	v_mfma_f32_16x16x32_bf16 v[28:31], v[148:151], v[196:199], v[28:31]
	v_mfma_f32_16x16x32_bf16 v[24:27], v[156:159], v[196:199], v[24:27]
	v_mfma_f32_16x16x32_bf16 v[12:15], v[148:151], v[204:207], v[12:15]
	v_mfma_f32_16x16x32_bf16 v[8:11], v[156:159], v[204:207], v[8:11]
	v_mfma_f32_16x16x32_bf16 v[52:55], v[160:163], v[176:179], v[52:55]
	v_mfma_f32_16x16x32_bf16 v[48:51], v[168:171], v[176:179], v[48:51]
	v_mfma_f32_16x16x32_bf16 v[36:39], v[160:163], v[184:187], v[36:39]
	v_mfma_f32_16x16x32_bf16 v[32:35], v[168:171], v[184:187], v[32:35]
	v_mfma_f32_16x16x32_bf16 v[20:23], v[160:163], v[192:195], v[20:23]
	v_mfma_f32_16x16x32_bf16 v[16:19], v[168:171], v[192:195], v[16:19]
	v_mfma_f32_16x16x32_bf16 v[4:7], v[160:163], v[200:203], v[4:7]
	v_mfma_f32_16x16x32_bf16 v[0:3], v[168:171], v[200:203], v[0:3]
	v_mfma_f32_16x16x32_bf16 v[52:55], v[164:167], v[180:183], v[52:55]
	v_mfma_f32_16x16x32_bf16 v[48:51], v[172:175], v[180:183], v[48:51]
	v_mfma_f32_16x16x32_bf16 v[36:39], v[164:167], v[188:191], v[36:39]
	v_mfma_f32_16x16x32_bf16 v[32:35], v[172:175], v[188:191], v[32:35]
	v_mfma_f32_16x16x32_bf16 v[20:23], v[164:167], v[196:199], v[20:23]
	v_mfma_f32_16x16x32_bf16 v[16:19], v[172:175], v[196:199], v[16:19]
	v_mfma_f32_16x16x32_bf16 v[4:7], v[164:167], v[204:207], v[4:7]
	v_mfma_f32_16x16x32_bf16 v[0:3], v[172:175], v[204:207], v[0:3]
	s_barrier
	s_add_i32 s59, s59, 2
	s_add_u32 s56, s56, 0x100
	s_addc_u32 s57, s57, 0
	s_cmp_gt_u32 s59, 61
	s_mov_b64 s[24:25], s[26:27]
	s_cbranch_scc0 .LBB0_3554
	s_and_b64 vcc, exec, s[10:11]
	s_cbranch_vccz .LBB0_3557
	s_barrier

; #define PG8_WAIT_V(n) asm volatile("s_waitcnt vmcnt(" #n ")" ::: "memory")
; #define PG8_WAIT_L(n) asm volatile("s_waitcnt lgkmcnt(" #n ")" ::: "memory")
; #define PG8_BAR __builtin_amdgcn_s_barrier()
; #define PG8_SCHED __builtin_amdgcn_sched_barrier(0)
;     ...
;         for (int t = 0; t < nt; t += 2) {
;             const bool last = (t == nt - 2);
;             const char* a1 = cA + (size_t)(t + 1) * kstep;
;             const char* a2 = last ? nA : cA + (size_t)(t + 2) * kstep; const char* b2 = last ? nB : cB + (size_t)(t + 2) * kstep;
;             const char* a3 = a2 + kstep; const char* b3 = b2 + kstep;
;             if (last && has_next) S.a_ready(nxt);
;             if constexpr (SP2) {
;             PG8_LDB(B0, 0, 0); PG8_LDB(B1, 0, 1); PG8_SCHED; PG8_LDA(At, 0, 0); PG8_STAGE(PG8_SA(1, 1), a1 + hstepA, voffA);
;             PG8_WAIT_V(8); PG8_WAIT_L(0); PG8_BAR; PG8_MMA(0, 0, At, B0); PG8_MMA(0, 1, At, B1); PG8_BAR; PG8_SCHED;
;             if constexpr (!HALFU) PG8_LDA(At, 0, 1); PG8_STAGE(PG8_SB(0, 0), b2, voffB); PG8_STAGE(PG8_SB(0, 1), b2 + hstep, voffB); PG8_STAGE(PG8_SA(0, 0), a2, voffA);
;             PG8_WAIT_V(8); PG8_WAIT_L(0); PG8_BAR; if constexpr (!HALFU) { PG8_MMA(1, 0, At, B0); PG8_MMA(1, 1, At, B1); } PG8_BAR; PG8_SCHED;
.LBB0_3640:
	s_sub_u32 s98, s10, 0x158000
	s_subb_u32 s99, s11, 0
	s_mov_b32 m0, s42
	s_nop 0
	global_load_lds_dwordx4 v128, s[98:99]
	s_mov_b32 m0, s43
	s_nop 0
	global_load_lds_dwordx4 v130, s[98:99]
	ds_read_b128 v[142:145], v137
	ds_read_b128 v[146:149], v137 offset:1024
	ds_read_b128 v[150:153], v137 offset:2048
	ds_read_b128 v[154:157], v137 offset:3072
	ds_read_b128 v[158:161], v138
	ds_read_b128 v[162:165], v138 offset:1024
	ds_read_b128 v[166:169], v138 offset:2048
	ds_read_b128 v[170:173], v138 offset:3072
	s_cmpk_eq_i32 s55, 0x52
	s_cselect_b32 s28, s6, s51
	s_cselect_b32 s29, s7, s52
	s_cselect_b32 s26, s22, s53
	s_cselect_b32 s27, s23, s54
	s_add_u32 s24, s28, 0x80
	s_addc_u32 s25, s29, 0
	s_add_i32 m0, s33, 0xc000
	ds_read_b128 v[174:177], v139
	ds_read_b128 v[178:181], v139 offset:1024
	ds_read_b128 v[182:185], v139 offset:2048
	ds_read_b128 v[186:189], v139 offset:3072
	ds_read_b128 v[190:193], v139 offset:4096
	ds_read_b128 v[194:197], v139 offset:5120
	ds_read_b128 v[198:201], v139 offset:6144
	ds_read_b128 v[202:205], v139 offset:7168
	global_load_lds_dwordx4 v128, s[10:11]
	s_add_i32 m0, s33, 0xe000
	s_nop 0
	global_load_lds_dwordx4 v130, s[10:11]
	s_waitcnt vmcnt(8) lgkmcnt(0)
	s_barrier
	v_mfma_scale_f32_16x16x128_f8f6f4 v[124:127], v[142:149], v[174:181], v[124:127], v140, v140 op_sel_hi:[0,0,0]
	v_mfma_scale_f32_16x16x128_f8f6f4 v[120:123], v[150:157], v[174:181], v[120:123], v140, v140 op_sel_hi:[0,0,0]
	v_mfma_scale_f32_16x16x128_f8f6f4 v[112:115], v[142:149], v[182:189], v[112:115], v140, v140 op_sel_hi:[0,0,0]
	v_mfma_scale_f32_16x16x128_f8f6f4 v[104:107], v[150:157], v[182:189], v[104:107], v140, v140 op_sel_hi:[0,0,0]
	v_mfma_scale_f32_16x16x128_f8f6f4 v[96:99], v[142:149], v[190:197], v[96:99], v140, v140 op_sel_hi:[0,0,0]
	v_mfma_scale_f32_16x16x128_f8f6f4 v[206:209], v[150:157], v[190:197], v[88:91], v140, v140 op_sel_hi:[0,0,0]
	v_mfma_scale_f32_16x16x128_f8f6f4 v[210:213], v[142:149], v[198:205], v[80:83], v140, v140 op_sel_hi:[0,0,0]
	v_mfma_scale_f32_16x16x128_f8f6f4 v[214:217], v[150:157], v[198:205], v[72:75], v140, v140 op_sel_hi:[0,0,0]
	v_mfma_scale_f32_16x16x128_f8f6f4 v[116:119], v[158:165], v[174:181], v[116:119], v140, v140 op_sel_hi:[0,0,0]
	v_mfma_scale_f32_16x16x128_f8f6f4 v[108:111], v[166:173], v[174:181], v[108:111], v140, v140 op_sel_hi:[0,0,0]
	v_mfma_scale_f32_16x16x128_f8f6f4 v[100:103], v[158:165], v[182:189], v[100:103], v140, v140 op_sel_hi:[0,0,0]
	v_mfma_scale_f32_16x16x128_f8f6f4 v[174:177], v[166:173], v[182:189], v[92:95], v140, v140 op_sel_hi:[0,0,0]
	v_mfma_scale_f32_16x16x128_f8f6f4 v[178:181], v[158:165], v[190:197], v[84:87], v140, v140 op_sel_hi:[0,0,0]
	v_mfma_scale_f32_16x16x128_f8f6f4 v[182:185], v[166:173], v[190:197], v[76:79], v140, v140 op_sel_hi:[0,0,0]
	v_mfma_scale_f32_16x16x128_f8f6f4 v[186:189], v[158:165], v[198:205], v[68:71], v140, v140 op_sel_hi:[0,0,0]
	v_mfma_scale_f32_16x16x128_f8f6f4 v[190:193], v[166:173], v[198:205], v[64:67], v140, v140 op_sel_hi:[0,0,0]
	s_barrier
	s_add_i32 s56, s45, s30
	s_mov_b32 m0, s56
	s_nop 1
	ds_read_b128 v[64:67], v139 offset:16384
	ds_read_b128 v[68:71], v139 offset:17408
	ds_read_b128 v[72:75], v139 offset:18432
	ds_read_b128 v[76:79], v139 offset:19456
	ds_read_b128 v[80:83], v139 offset:20480
	ds_read_b128 v[84:87], v139 offset:21504
	ds_read_b128 v[88:91], v139 offset:22528
	ds_read_b128 v[92:95], v139 offset:23552
	global_load_lds_dwordx4 v128, s[26:27]
	s_add_i32 m0, s56, 0x2000
	s_add_u32 s56, s26, 0x158000
	s_addc_u32 s57, s27, 0
	s_add_i32 s58, s46, s30
	global_load_lds_dwordx4 v130, s[26:27]
	s_mov_b32 m0, s58
	s_nop 0
	global_load_lds_dwordx4 v128, s[56:57]
	s_add_i32 m0, s58, 0x2000
	s_nop 0
	global_load_lds_dwordx4 v130, s[56:57]
	s_waitcnt vmcnt(4) lgkmcnt(0)
	s_barrier
	v_mfma_scale_f32_16x16x128_f8f6f4 v[60:63], v[142:149], v[64:71], v[60:63], v140, v140 op_sel_hi:[0,0,0]
	v_mfma_scale_f32_16x16x128_f8f6f4 v[56:59], v[150:157], v[64:71], v[56:59], v140, v140 op_sel_hi:[0,0,0]
	v_mfma_scale_f32_16x16x128_f8f6f4 v[48:51], v[142:149], v[72:79], v[48:51], v140, v140 op_sel_hi:[0,0,0]
	v_mfma_scale_f32_16x16x128_f8f6f4 v[194:197], v[150:157], v[72:79], v[40:43], v140, v140 op_sel_hi:[0,0,0]
	v_mfma_scale_f32_16x16x128_f8f6f4 v[198:201], v[142:149], v[80:87], v[32:35], v140, v140 op_sel_hi:[0,0,0]
	v_mfma_scale_f32_16x16x128_f8f6f4 v[202:205], v[150:157], v[80:87], v[24:27], v140, v140 op_sel_hi:[0,0,0]
	v_mfma_scale_f32_16x16x128_f8f6f4 v[218:221], v[142:149], v[88:95], v[16:19], v140, v140 op_sel_hi:[0,0,0]
	v_mfma_scale_f32_16x16x128_f8f6f4 v[222:225], v[150:157], v[88:95], v[8:11], v140, v140 op_sel_hi:[0,0,0]
	v_mfma_scale_f32_16x16x128_f8f6f4 v[52:55], v[158:165], v[64:71], v[52:55], v140, v140 op_sel_hi:[0,0,0]
	v_mfma_scale_f32_16x16x128_f8f6f4 v[226:229], v[166:173], v[64:71], v[44:47], v140, v140 op_sel_hi:[0,0,0]
	v_mfma_scale_f32_16x16x128_f8f6f4 v[230:233], v[158:165], v[72:79], v[36:39], v140, v140 op_sel_hi:[0,0,0]
	v_mfma_scale_f32_16x16x128_f8f6f4 v[234:237], v[166:173], v[72:79], v[28:31], v140, v140 op_sel_hi:[0,0,0]
	v_mfma_scale_f32_16x16x128_f8f6f4 v[238:241], v[158:165], v[80:87], v[20:23], v140, v140 op_sel_hi:[0,0,0]
	v_mfma_scale_f32_16x16x128_f8f6f4 v[242:245], v[166:173], v[80:87], v[12:15], v140, v140 op_sel_hi:[0,0,0]
	v_mfma_scale_f32_16x16x128_f8f6f4 v[246:249], v[158:165], v[88:95], v[4:7], v140, v140 op_sel_hi:[0,0,0]
	v_mfma_scale_f32_16x16x128_f8f6f4 v[250:253], v[166:173], v[88:95], v[0:3], v140, v140 op_sel_hi:[0,0,0]
	s_barrier
; #define PG8_WAIT_V(n) asm volatile("s_waitcnt vmcnt(" #n ")" ::: "memory")
; #define PG8_WAIT_L(n) asm volatile("s_waitcnt lgkmcnt(" #n ")" ::: "memory")
; #define PG8_BAR __builtin_amdgcn_s_barrier()
; #define PG8_SCHED __builtin_amdgcn_sched_barrier(0)
;     ...
;             PG8_LDB(B0, 1, 0); PG8_LDB(B1, 1, 1); PG8_SCHED; PG8_LDA(At, 1, 0); PG8_STAGE(PG8_SA(0, 1), a2 + hstepA, voffA);
;             PG8_WAIT_V(8); PG8_WAIT_L(0); PG8_BAR; PG8_MMA(0, 0, At, B0); PG8_MMA(0, 1, At, B1); PG8_BAR; PG8_SCHED;
;             if constexpr (!HALFU) PG8_LDA(At, 1, 1); PG8_STAGE(PG8_SB(1, 0), b3, voffB); PG8_STAGE(PG8_SB(1, 1), b3 + hstep, voffB); PG8_STAGE(PG8_SA(1, 0), a3, voffA);
;             PG8_WAIT_V(8); PG8_WAIT_L(0); PG8_BAR; if constexpr (!HALFU) { PG8_MMA(1, 0, At, B0); PG8_MMA(1, 1, At, B1); } PG8_BAR; PG8_SCHED;
;     ...
;         if constexpr (ALIGN_EPI) { if (wr == 0) PG8_BAR; }
	s_mov_b32 m0, s33
	s_nop 0
	global_load_lds_dwordx4 v128, s[28:29]
	s_mov_b32 m0, s36
	s_nop 0
	global_load_lds_dwordx4 v130, s[28:29]
	s_add_i32 s56, 0, 0x18000
	s_add_i32 s57, 0, 0x1c000
	s_nop 0
	v_add_u32_e32 v12, s56, v136
	v_add_u32_e32 v16, s57, v136
	ds_read_b128 v[0:3], v12
	ds_read_b128 v[4:7], v12 offset:1024
	ds_read_b128 v[8:11], v12 offset:2048
	ds_read_b128 v[12:15], v12 offset:3072
	ds_read_b128 v[142:145], v16
	ds_read_b128 v[146:149], v16 offset:1024
	ds_read_b128 v[150:153], v16 offset:2048
	ds_read_b128 v[154:157], v16 offset:3072
	s_add_u32 s28, s28, 0x158000
	s_addc_u32 s29, s29, 0
	s_mov_b32 m0, s37
	ds_read_b128 v[16:19], v139 offset:32768
	ds_read_b128 v[20:23], v139 offset:33792
	ds_read_b128 v[24:27], v139 offset:34816
	ds_read_b128 v[28:31], v139 offset:35840
	ds_read_b128 v[32:35], v139 offset:36864
	ds_read_b128 v[36:39], v139 offset:37888
	ds_read_b128 v[40:43], v139 offset:38912
	ds_read_b128 v[44:47], v139 offset:39936
	global_load_lds_dwordx4 v128, s[28:29]
	s_mov_b32 m0, s38
	s_nop 0
	global_load_lds_dwordx4 v130, s[28:29]
	s_waitcnt vmcnt(8) lgkmcnt(0)
	s_barrier
	v_mfma_scale_f32_16x16x128_f8f6f4 v[124:127], v[0:7], v[16:23], v[124:127], v140, v140 op_sel_hi:[0,0,0]
	v_mfma_scale_f32_16x16x128_f8f6f4 v[120:123], v[8:15], v[16:23], v[120:123], v140, v140 op_sel_hi:[0,0,0]
	v_mfma_scale_f32_16x16x128_f8f6f4 v[112:115], v[0:7], v[24:31], v[112:115], v140, v140 op_sel_hi:[0,0,0]
	v_mfma_scale_f32_16x16x128_f8f6f4 v[104:107], v[8:15], v[24:31], v[104:107], v140, v140 op_sel_hi:[0,0,0]
	v_mfma_scale_f32_16x16x128_f8f6f4 v[96:99], v[0:7], v[32:39], v[96:99], v140, v140 op_sel_hi:[0,0,0]
	v_mfma_scale_f32_16x16x128_f8f6f4 v[88:91], v[8:15], v[32:39], v[206:209], v140, v140 op_sel_hi:[0,0,0]
	v_mfma_scale_f32_16x16x128_f8f6f4 v[80:83], v[0:7], v[40:47], v[210:213], v140, v140 op_sel_hi:[0,0,0]
	v_mfma_scale_f32_16x16x128_f8f6f4 v[72:75], v[8:15], v[40:47], v[214:217], v140, v140 op_sel_hi:[0,0,0]
	v_mfma_scale_f32_16x16x128_f8f6f4 v[116:119], v[142:149], v[16:23], v[116:119], v140, v140 op_sel_hi:[0,0,0]
	v_mfma_scale_f32_16x16x128_f8f6f4 v[108:111], v[150:157], v[16:23], v[108:111], v140, v140 op_sel_hi:[0,0,0]
	v_mfma_scale_f32_16x16x128_f8f6f4 v[100:103], v[142:149], v[24:31], v[100:103], v140, v140 op_sel_hi:[0,0,0]
	v_mfma_scale_f32_16x16x128_f8f6f4 v[92:95], v[150:157], v[24:31], v[174:177], v140, v140 op_sel_hi:[0,0,0]
	v_mfma_scale_f32_16x16x128_f8f6f4 v[84:87], v[142:149], v[32:39], v[178:181], v140, v140 op_sel_hi:[0,0,0]
	v_mfma_scale_f32_16x16x128_f8f6f4 v[76:79], v[150:157], v[32:39], v[182:185], v140, v140 op_sel_hi:[0,0,0]
	v_mfma_scale_f32_16x16x128_f8f6f4 v[68:71], v[142:149], v[40:47], v[186:189], v140, v140 op_sel_hi:[0,0,0]
	v_mfma_scale_f32_16x16x128_f8f6f4 v[64:67], v[150:157], v[40:47], v[190:193], v140, v140 op_sel_hi:[0,0,0]
	s_barrier
	s_add_u32 s28, s26, 0x80
	s_addc_u32 s29, s27, 0
	s_add_i32 s56, s56, s30
	s_mov_b32 m0, s56
	ds_read_b128 v[158:161], v139 offset:49152
	ds_read_b128 v[162:165], v139 offset:50176
	ds_read_b128 v[166:169], v139 offset:51200
	ds_read_b128 v[170:173], v139 offset:52224
	ds_read_b128 v[174:177], v139 offset:53248
	ds_read_b128 v[178:181], v139 offset:54272
	ds_read_b128 v[182:185], v139 offset:55296
	ds_read_b128 v[186:189], v139 offset:56320
	global_load_lds_dwordx4 v128, s[28:29]
	s_add_i32 m0, s56, 0x2000
	s_add_u32 s26, s26, 0x158080
	v_lshl_add_u64 v[16:17], s[28:29], 0, v[130:131]
	s_addc_u32 s27, s27, 0
	s_add_i32 s28, s57, s30
	global_load_lds_dwordx4 v[16:17], off
	s_mov_b32 m0, s28
	s_nop 0
	global_load_lds_dwordx4 v128, s[26:27]
	s_add_i32 m0, s28, 0x2000
	s_nop 0
	global_load_lds_dwordx4 v130, s[26:27]
	s_waitcnt vmcnt(4) lgkmcnt(0)
	s_barrier
	v_mfma_scale_f32_16x16x128_f8f6f4 v[60:63], v[0:7], v[158:165], v[60:63], v140, v140 op_sel_hi:[0,0,0]
	v_mfma_scale_f32_16x16x128_f8f6f4 v[56:59], v[8:15], v[158:165], v[56:59], v140, v140 op_sel_hi:[0,0,0]
	v_mfma_scale_f32_16x16x128_f8f6f4 v[48:51], v[0:7], v[166:173], v[48:51], v140, v140 op_sel_hi:[0,0,0]
	v_mfma_scale_f32_16x16x128_f8f6f4 v[40:43], v[8:15], v[166:173], v[194:197], v140, v140 op_sel_hi:[0,0,0]
	v_mfma_scale_f32_16x16x128_f8f6f4 v[32:35], v[0:7], v[174:181], v[198:201], v140, v140 op_sel_hi:[0,0,0]
	v_mfma_scale_f32_16x16x128_f8f6f4 v[24:27], v[8:15], v[174:181], v[202:205], v140, v140 op_sel_hi:[0,0,0]
	v_mfma_scale_f32_16x16x128_f8f6f4 v[16:19], v[0:7], v[182:189], v[218:221], v140, v140 op_sel_hi:[0,0,0]
	v_mfma_scale_f32_16x16x128_f8f6f4 v[8:11], v[8:15], v[182:189], v[222:225], v140, v140 op_sel_hi:[0,0,0]
	v_mfma_scale_f32_16x16x128_f8f6f4 v[52:55], v[142:149], v[158:165], v[52:55], v140, v140 op_sel_hi:[0,0,0]
	v_mfma_scale_f32_16x16x128_f8f6f4 v[44:47], v[150:157], v[158:165], v[226:229], v140, v140 op_sel_hi:[0,0,0]
	v_mfma_scale_f32_16x16x128_f8f6f4 v[36:39], v[142:149], v[166:173], v[230:233], v140, v140 op_sel_hi:[0,0,0]
	v_mfma_scale_f32_16x16x128_f8f6f4 v[28:31], v[150:157], v[166:173], v[234:237], v140, v140 op_sel_hi:[0,0,0]
	v_mfma_scale_f32_16x16x128_f8f6f4 v[20:23], v[142:149], v[174:181], v[238:241], v140, v140 op_sel_hi:[0,0,0]
	v_mfma_scale_f32_16x16x128_f8f6f4 v[12:15], v[150:157], v[174:181], v[242:245], v140, v140 op_sel_hi:[0,0,0]
	v_mfma_scale_f32_16x16x128_f8f6f4 v[4:7], v[142:149], v[182:189], v[246:249], v140, v140 op_sel_hi:[0,0,0]
	v_mfma_scale_f32_16x16x128_f8f6f4 v[0:3], v[150:157], v[182:189], v[250:253], v140, v140 op_sel_hi:[0,0,0]
	s_barrier
	s_add_i32 s55, s55, 2
	s_add_u32 s51, s51, 0x100
	s_addc_u32 s52, s52, 0
	s_add_u32 s53, s53, 0x100
	s_addc_u32 s54, s54, 0
	s_add_u32 s10, s10, 0x100
	s_addc_u32 s11, s11, 0
	s_cmpk_gt_u32 s55, 0x53
	s_cbranch_scc0 .LBB0_3640
	s_and_b64 vcc, exec, s[12:13]
	s_cbranch_vccz .LBB0_3643
	s_barrier
